# peeled first K-iteration in the 7 non-hook GEMM loops: first MFMA into each accumulator takes C=0, per-tile accumulator zeroing (128 v_mov/wave) removed
# speedup vs baseline: 1.0098x; 1.0098x over previous
.LBB0_130:
	s_ashr_i32 s23, s22, 31
	s_lshl_b64 s[24:25], s[22:23], 19
	s_add_u32 s24, s36, s24
	s_addc_u32 s25, s37, s25
	s_and_b64 s[26:27], s[6:7], exec
	s_cselect_b32 s23, s25, s9
	s_cselect_b32 s58, s24, s8
	s_ashr_i32 s21, s20, 31
	s_lshl_b64 s[26:27], s[20:21], 19
	s_add_u32 s26, s38, s26
	s_addc_u32 s27, s39, s27
	s_and_b64 s[28:29], s[6:7], exec
	s_cselect_b32 s21, s27, s11
	s_cselect_b32 s59, s26, s10
	s_add_u32 s68, s58, 0x80
	s_addc_u32 s69, s23, 0
	s_add_u32 s28, s8, 0x40080
	s_addc_u32 s29, s9, 0
	s_add_u32 s70, s10, 0x100
	v_lshl_add_u64 v[142:143], s[28:29], 0, v[138:139]
	v_lshl_add_u64 v[144:145], s[28:29], 0, v[140:141]
	s_addc_u32 s71, s11, 0
	s_mov_b32 s72, -2
	s_mov_b64 s[10:11], 0
	s_add_u32 s28, s8, s10
	s_addc_u32 s29, s9, s11
	s_add_u32 s34, s28, 0x100
	s_addc_u32 s35, s29, 0
	s_add_u32 s30, s70, s10
	s_addc_u32 s31, s71, s11
	s_add_u32 s28, s28, 0x180
	s_addc_u32 s29, s29, 0
	s_add_i32 s73, 0, 0x10000
	s_add_i32 s76, 0, 0x14000
	v_add_u32_e32 v146, s73, v166
	ds_read_b128 v[148:151], v146
	ds_read_b128 v[152:155], v146 offset:1024
	ds_read_b128 v[156:159], v146 offset:2048
	ds_read_b128 v[160:163], v146 offset:3072
	v_add_u32_e32 v146, s76, v166
	ds_read_b128 v[172:175], v146
	ds_read_b128 v[176:179], v146 offset:1024
	ds_read_b128 v[180:183], v146 offset:2048
	ds_read_b128 v[184:187], v146 offset:3072
	s_cmpk_eq_i32 s10, 0x700
	s_cselect_b32 s29, s69, s29
	s_cselect_b32 s28, s68, s28
	s_cselect_b32 s31, s21, s31
	s_cselect_b32 s30, s59, s30
	s_cselect_b32 s35, s23, s35
	s_cselect_b32 s34, s58, s34
	v_lshl_add_u64 v[164:165], v[142:143], 0, s[10:11]
	s_add_i32 m0, s41, 0xc000
	ds_read_b128 v[188:191], v171
	ds_read_b128 v[202:205], v171 offset:1024
	ds_read_b128 v[206:209], v171 offset:2048
	ds_read_b128 v[210:213], v171 offset:3072
	ds_read_b128 v[214:217], v171 offset:4096
	ds_read_b128 v[218:221], v171 offset:5120
	ds_read_b128 v[222:225], v171 offset:6144
	ds_read_b128 v[226:229], v171 offset:7168
	global_load_lds_dwordx4 v[164:165], off
	v_lshl_add_u64 v[164:165], v[144:145], 0, s[10:11]
	s_add_i32 m0, s41, 0xe000
	s_nop 0
	global_load_lds_dwordx4 v[164:165], off
	s_waitcnt vmcnt(8)
	s_waitcnt lgkmcnt(0)
	s_setprio 1
	s_barrier
	v_mfma_f32_16x16x32_bf16 v[126:129], v[148:151], v[188:191], 0
	v_mfma_f32_16x16x32_bf16 v[122:125], v[156:159], v[188:191], 0
	v_mfma_f32_16x16x32_bf16 v[110:113], v[148:151], v[206:209], 0
	v_mfma_f32_16x16x32_bf16 v[106:109], v[156:159], v[206:209], 0
	v_mfma_f32_16x16x32_bf16 v[94:97], v[148:151], v[214:217], 0
	v_mfma_f32_16x16x32_bf16 v[90:93], v[156:159], v[214:217], 0
	v_mfma_f32_16x16x32_bf16 v[78:81], v[148:151], v[222:225], 0
	v_mfma_f32_16x16x32_bf16 v[74:77], v[156:159], v[222:225], 0
	v_mfma_f32_16x16x32_bf16 v[126:129], v[152:155], v[202:205], v[126:129]
	v_mfma_f32_16x16x32_bf16 v[122:125], v[160:163], v[202:205], v[122:125]
	v_mfma_f32_16x16x32_bf16 v[110:113], v[152:155], v[210:213], v[110:113]
	v_mfma_f32_16x16x32_bf16 v[106:109], v[160:163], v[210:213], v[106:109]
	v_mfma_f32_16x16x32_bf16 v[94:97], v[152:155], v[218:221], v[94:97]
	v_mfma_f32_16x16x32_bf16 v[90:93], v[160:163], v[218:221], v[90:93]
	v_mfma_f32_16x16x32_bf16 v[78:81], v[152:155], v[226:229], v[78:81]
	v_mfma_f32_16x16x32_bf16 v[74:77], v[160:163], v[226:229], v[74:77]
	v_mfma_f32_16x16x32_bf16 v[118:121], v[172:175], v[188:191], 0
	v_mfma_f32_16x16x32_bf16 v[114:117], v[180:183], v[188:191], 0
	v_mfma_f32_16x16x32_bf16 v[102:105], v[172:175], v[206:209], 0
	v_mfma_f32_16x16x32_bf16 v[98:101], v[180:183], v[206:209], 0
	v_mfma_f32_16x16x32_bf16 v[86:89], v[172:175], v[214:217], 0
	v_mfma_f32_16x16x32_bf16 v[82:85], v[180:183], v[214:217], 0
	v_mfma_f32_16x16x32_bf16 v[70:73], v[172:175], v[222:225], 0
	v_mfma_f32_16x16x32_bf16 v[66:69], v[180:183], v[222:225], 0
	v_mfma_f32_16x16x32_bf16 v[118:121], v[176:179], v[202:205], v[118:121]
	v_mfma_f32_16x16x32_bf16 v[114:117], v[184:187], v[202:205], v[114:117]
	v_mfma_f32_16x16x32_bf16 v[102:105], v[176:179], v[210:213], v[102:105]
	v_mfma_f32_16x16x32_bf16 v[98:101], v[184:187], v[210:213], v[98:101]
	v_mfma_f32_16x16x32_bf16 v[86:89], v[176:179], v[218:221], v[86:89]
	v_mfma_f32_16x16x32_bf16 v[82:85], v[184:187], v[218:221], v[82:85]
	v_mfma_f32_16x16x32_bf16 v[70:73], v[176:179], v[226:229], v[70:73]
	v_mfma_f32_16x16x32_bf16 v[66:69], v[184:187], v[226:229], v[66:69]
	s_barrier
	s_setprio 0
	s_add_i32 s73, s73, s40
	v_lshl_add_u64 v[164:165], s[30:31], 0, v[134:135]
	s_mov_b32 m0, s73
	ds_read_b128 v[188:191], v171 offset:16384
	ds_read_b128 v[202:205], v171 offset:17408
	ds_read_b128 v[206:209], v171 offset:18432
	ds_read_b128 v[210:213], v171 offset:19456
	ds_read_b128 v[214:217], v171 offset:20480
	ds_read_b128 v[218:221], v171 offset:21504
	ds_read_b128 v[222:225], v171 offset:22528
	ds_read_b128 v[226:229], v171 offset:23552
	global_load_lds_dwordx4 v[164:165], off
	s_add_i32 m0, s73, 0x2000
	s_add_u32 s74, s30, 0x40000
	v_lshl_add_u64 v[192:193], s[30:31], 0, v[130:131]
	s_addc_u32 s75, s31, 0
	s_add_i32 s73, s76, s40
	global_load_lds_dwordx4 v[192:193], off
	v_lshl_add_u64 v[194:195], s[74:75], 0, v[134:135]
	s_mov_b32 m0, s73
	s_nop 0
	global_load_lds_dwordx4 v[194:195], off
	v_lshl_add_u64 v[194:195], s[74:75], 0, v[130:131]
	s_add_i32 m0, s73, 0x2000
	s_nop 0
	global_load_lds_dwordx4 v[194:195], off
	v_lshl_add_u64 v[194:195], s[34:35], 0, v[136:137]
	s_mov_b32 m0, s41
	s_nop 0
	global_load_lds_dwordx4 v[194:195], off
	v_lshl_add_u64 v[194:195], s[34:35], 0, v[132:133]
	s_mov_b32 m0, s42
	s_nop 0
	global_load_lds_dwordx4 v[194:195], off
	s_waitcnt vmcnt(8)
	s_waitcnt lgkmcnt(0)
	s_setprio 1
	s_barrier
	v_mfma_f32_16x16x32_bf16 v[62:65], v[148:151], v[188:191], 0
	v_mfma_f32_16x16x32_bf16 v[58:61], v[156:159], v[188:191], 0
	v_mfma_f32_16x16x32_bf16 v[46:49], v[148:151], v[206:209], 0
	v_mfma_f32_16x16x32_bf16 v[42:45], v[156:159], v[206:209], 0
	v_mfma_f32_16x16x32_bf16 v[30:33], v[148:151], v[214:217], 0
	v_mfma_f32_16x16x32_bf16 v[26:29], v[156:159], v[214:217], 0
	v_mfma_f32_16x16x32_bf16 v[14:17], v[148:151], v[222:225], 0
	v_mfma_f32_16x16x32_bf16 v[10:13], v[156:159], v[222:225], 0
	v_mfma_f32_16x16x32_bf16 v[62:65], v[152:155], v[202:205], v[62:65]
	v_mfma_f32_16x16x32_bf16 v[58:61], v[160:163], v[202:205], v[58:61]
	v_mfma_f32_16x16x32_bf16 v[46:49], v[152:155], v[210:213], v[46:49]
	v_mfma_f32_16x16x32_bf16 v[42:45], v[160:163], v[210:213], v[42:45]
	v_mfma_f32_16x16x32_bf16 v[30:33], v[152:155], v[218:221], v[30:33]
	v_mfma_f32_16x16x32_bf16 v[26:29], v[160:163], v[218:221], v[26:29]
	v_mfma_f32_16x16x32_bf16 v[14:17], v[152:155], v[226:229], v[14:17]
	v_mfma_f32_16x16x32_bf16 v[10:13], v[160:163], v[226:229], v[10:13]
	v_mfma_f32_16x16x32_bf16 v[54:57], v[172:175], v[188:191], 0
	v_mfma_f32_16x16x32_bf16 v[50:53], v[180:183], v[188:191], 0
	v_mfma_f32_16x16x32_bf16 v[38:41], v[172:175], v[206:209], 0
	v_mfma_f32_16x16x32_bf16 v[34:37], v[180:183], v[206:209], 0
	v_mfma_f32_16x16x32_bf16 v[22:25], v[172:175], v[214:217], 0
	v_mfma_f32_16x16x32_bf16 v[18:21], v[180:183], v[214:217], 0
	v_mfma_f32_16x16x32_bf16 v[6:9], v[172:175], v[222:225], 0
	v_mfma_f32_16x16x32_bf16 v[2:5], v[180:183], v[222:225], 0
	v_mfma_f32_16x16x32_bf16 v[54:57], v[176:179], v[202:205], v[54:57]
	v_mfma_f32_16x16x32_bf16 v[50:53], v[184:187], v[202:205], v[50:53]
	v_mfma_f32_16x16x32_bf16 v[38:41], v[176:179], v[210:213], v[38:41]
	v_mfma_f32_16x16x32_bf16 v[34:37], v[184:187], v[210:213], v[34:37]
	v_mfma_f32_16x16x32_bf16 v[22:25], v[176:179], v[218:221], v[22:25]
	v_mfma_f32_16x16x32_bf16 v[18:21], v[184:187], v[218:221], v[18:21]
	v_mfma_f32_16x16x32_bf16 v[6:9], v[176:179], v[226:229], v[6:9]
	v_mfma_f32_16x16x32_bf16 v[2:5], v[184:187], v[226:229], v[2:5]
	s_barrier
	s_setprio 0
	s_add_i32 s73, 0, 0x18000
	v_add_u32_e32 v146, s73, v166
	s_add_i32 s74, 0, 0x1c000
	ds_read_b128 v[148:151], v146
	ds_read_b128 v[152:155], v146 offset:1024
	ds_read_b128 v[156:159], v146 offset:2048
	ds_read_b128 v[160:163], v146 offset:3072
	v_add_u32_e32 v146, s74, v166
	ds_read_b128 v[172:175], v146
	ds_read_b128 v[176:179], v146 offset:1024
	ds_read_b128 v[180:183], v146 offset:2048
	ds_read_b128 v[184:187], v146 offset:3072
	s_add_u32 s34, s34, 0x40000
	s_addc_u32 s35, s35, 0
	s_mov_b32 m0, s43
	v_lshl_add_u64 v[194:195], s[34:35], 0, v[136:137]
	ds_read_b128 v[188:191], v171 offset:32768
	ds_read_b128 v[202:205], v171 offset:33792
	ds_read_b128 v[206:209], v171 offset:34816
	ds_read_b128 v[210:213], v171 offset:35840
	ds_read_b128 v[214:217], v171 offset:36864
	ds_read_b128 v[218:221], v171 offset:37888
	ds_read_b128 v[222:225], v171 offset:38912
	ds_read_b128 v[226:229], v171 offset:39936
	global_load_lds_dwordx4 v[194:195], off
	v_lshl_add_u64 v[194:195], s[34:35], 0, v[132:133]
	s_mov_b32 m0, s44
	s_nop 0
	global_load_lds_dwordx4 v[194:195], off
	s_waitcnt vmcnt(8)
	s_waitcnt lgkmcnt(0)
	s_setprio 1
	s_barrier
	v_mfma_f32_16x16x32_bf16 v[126:129], v[148:151], v[188:191], v[126:129]
	v_mfma_f32_16x16x32_bf16 v[122:125], v[156:159], v[188:191], v[122:125]
	v_mfma_f32_16x16x32_bf16 v[110:113], v[148:151], v[206:209], v[110:113]
	v_mfma_f32_16x16x32_bf16 v[106:109], v[156:159], v[206:209], v[106:109]
	v_mfma_f32_16x16x32_bf16 v[94:97], v[148:151], v[214:217], v[94:97]
	v_mfma_f32_16x16x32_bf16 v[90:93], v[156:159], v[214:217], v[90:93]
	v_mfma_f32_16x16x32_bf16 v[78:81], v[148:151], v[222:225], v[78:81]
	v_mfma_f32_16x16x32_bf16 v[74:77], v[156:159], v[222:225], v[74:77]
	v_mfma_f32_16x16x32_bf16 v[126:129], v[152:155], v[202:205], v[126:129]
	v_mfma_f32_16x16x32_bf16 v[122:125], v[160:163], v[202:205], v[122:125]
	v_mfma_f32_16x16x32_bf16 v[110:113], v[152:155], v[210:213], v[110:113]
	v_mfma_f32_16x16x32_bf16 v[106:109], v[160:163], v[210:213], v[106:109]
	v_mfma_f32_16x16x32_bf16 v[94:97], v[152:155], v[218:221], v[94:97]
	v_mfma_f32_16x16x32_bf16 v[90:93], v[160:163], v[218:221], v[90:93]
	v_mfma_f32_16x16x32_bf16 v[78:81], v[152:155], v[226:229], v[78:81]
	v_mfma_f32_16x16x32_bf16 v[74:77], v[160:163], v[226:229], v[74:77]
	v_mfma_f32_16x16x32_bf16 v[118:121], v[172:175], v[188:191], v[118:121]
	v_mfma_f32_16x16x32_bf16 v[114:117], v[180:183], v[188:191], v[114:117]
	v_mfma_f32_16x16x32_bf16 v[102:105], v[172:175], v[206:209], v[102:105]
	v_mfma_f32_16x16x32_bf16 v[98:101], v[180:183], v[206:209], v[98:101]
	v_mfma_f32_16x16x32_bf16 v[86:89], v[172:175], v[214:217], v[86:89]
	v_mfma_f32_16x16x32_bf16 v[82:85], v[180:183], v[214:217], v[82:85]
	v_mfma_f32_16x16x32_bf16 v[70:73], v[172:175], v[222:225], v[70:73]
	v_mfma_f32_16x16x32_bf16 v[66:69], v[180:183], v[222:225], v[66:69]
	v_mfma_f32_16x16x32_bf16 v[118:121], v[176:179], v[202:205], v[118:121]
	v_mfma_f32_16x16x32_bf16 v[114:117], v[184:187], v[202:205], v[114:117]
	v_mfma_f32_16x16x32_bf16 v[102:105], v[176:179], v[210:213], v[102:105]
	v_mfma_f32_16x16x32_bf16 v[98:101], v[184:187], v[210:213], v[98:101]
	v_mfma_f32_16x16x32_bf16 v[86:89], v[176:179], v[218:221], v[86:89]
	v_mfma_f32_16x16x32_bf16 v[82:85], v[184:187], v[218:221], v[82:85]
	v_mfma_f32_16x16x32_bf16 v[70:73], v[176:179], v[226:229], v[70:73]
	v_mfma_f32_16x16x32_bf16 v[66:69], v[184:187], v[226:229], v[66:69]
	s_barrier
	s_setprio 0
	s_add_i32 s34, s73, s40
	v_lshl_add_u64 v[164:165], v[164:165], 0, s[90:91]
	s_mov_b32 m0, s34
	ds_read_b128 v[188:191], v171 offset:49152
	ds_read_b128 v[202:205], v171 offset:50176
	ds_read_b128 v[206:209], v171 offset:51200
	ds_read_b128 v[210:213], v171 offset:52224
	ds_read_b128 v[214:217], v171 offset:53248
	ds_read_b128 v[218:221], v171 offset:54272
	ds_read_b128 v[222:225], v171 offset:55296
	ds_read_b128 v[226:229], v171 offset:56320
	global_load_lds_dwordx4 v[164:165], off
	s_add_i32 m0, s34, 0x2000
	s_add_u32 s30, s30, 0x40080
	v_lshl_add_u64 v[164:165], v[192:193], 0, s[90:91]
	s_addc_u32 s31, s31, 0
	s_add_i32 s34, s74, s40
	global_load_lds_dwordx4 v[164:165], off
	v_lshl_add_u64 v[164:165], s[30:31], 0, v[134:135]
	s_mov_b32 m0, s34
	s_nop 0
	global_load_lds_dwordx4 v[164:165], off
	v_lshl_add_u64 v[164:165], s[30:31], 0, v[130:131]
	s_add_i32 m0, s34, 0x2000
	s_nop 0
	global_load_lds_dwordx4 v[164:165], off
	v_lshl_add_u64 v[164:165], s[28:29], 0, v[136:137]
	s_mov_b32 m0, s45
	s_nop 0
	global_load_lds_dwordx4 v[164:165], off
	v_lshl_add_u64 v[164:165], s[28:29], 0, v[132:133]
	s_mov_b32 m0, s51
	s_nop 0
	global_load_lds_dwordx4 v[164:165], off
	s_waitcnt vmcnt(8)
	s_waitcnt lgkmcnt(0)
	s_setprio 1
	s_barrier
	v_mfma_f32_16x16x32_bf16 v[62:65], v[148:151], v[188:191], v[62:65]
	v_mfma_f32_16x16x32_bf16 v[58:61], v[156:159], v[188:191], v[58:61]
	v_mfma_f32_16x16x32_bf16 v[46:49], v[148:151], v[206:209], v[46:49]
	v_mfma_f32_16x16x32_bf16 v[42:45], v[156:159], v[206:209], v[42:45]
	v_mfma_f32_16x16x32_bf16 v[30:33], v[148:151], v[214:217], v[30:33]
	v_mfma_f32_16x16x32_bf16 v[26:29], v[156:159], v[214:217], v[26:29]
	v_mfma_f32_16x16x32_bf16 v[14:17], v[148:151], v[222:225], v[14:17]
	v_mfma_f32_16x16x32_bf16 v[10:13], v[156:159], v[222:225], v[10:13]
	v_mfma_f32_16x16x32_bf16 v[62:65], v[152:155], v[202:205], v[62:65]
	v_mfma_f32_16x16x32_bf16 v[58:61], v[160:163], v[202:205], v[58:61]
	v_mfma_f32_16x16x32_bf16 v[46:49], v[152:155], v[210:213], v[46:49]
	v_mfma_f32_16x16x32_bf16 v[42:45], v[160:163], v[210:213], v[42:45]
	v_mfma_f32_16x16x32_bf16 v[30:33], v[152:155], v[218:221], v[30:33]
	v_mfma_f32_16x16x32_bf16 v[26:29], v[160:163], v[218:221], v[26:29]
	v_mfma_f32_16x16x32_bf16 v[14:17], v[152:155], v[226:229], v[14:17]
	v_mfma_f32_16x16x32_bf16 v[10:13], v[160:163], v[226:229], v[10:13]
	v_mfma_f32_16x16x32_bf16 v[54:57], v[172:175], v[188:191], v[54:57]
	v_mfma_f32_16x16x32_bf16 v[50:53], v[180:183], v[188:191], v[50:53]
	v_mfma_f32_16x16x32_bf16 v[38:41], v[172:175], v[206:209], v[38:41]
	v_mfma_f32_16x16x32_bf16 v[34:37], v[180:183], v[206:209], v[34:37]
	v_mfma_f32_16x16x32_bf16 v[22:25], v[172:175], v[214:217], v[22:25]
	v_mfma_f32_16x16x32_bf16 v[18:21], v[180:183], v[214:217], v[18:21]
	v_mfma_f32_16x16x32_bf16 v[6:9], v[172:175], v[222:225], v[6:9]
	v_mfma_f32_16x16x32_bf16 v[2:5], v[180:183], v[222:225], v[2:5]
	v_mfma_f32_16x16x32_bf16 v[54:57], v[176:179], v[202:205], v[54:57]
	v_mfma_f32_16x16x32_bf16 v[50:53], v[184:187], v[202:205], v[50:53]
	v_mfma_f32_16x16x32_bf16 v[38:41], v[176:179], v[210:213], v[38:41]
	v_mfma_f32_16x16x32_bf16 v[34:37], v[184:187], v[210:213], v[34:37]
	v_mfma_f32_16x16x32_bf16 v[22:25], v[176:179], v[218:221], v[22:25]
	v_mfma_f32_16x16x32_bf16 v[18:21], v[184:187], v[218:221], v[18:21]
	v_mfma_f32_16x16x32_bf16 v[6:9], v[176:179], v[226:229], v[6:9]
	v_mfma_f32_16x16x32_bf16 v[2:5], v[184:187], v[226:229], v[2:5]
	s_barrier
	s_setprio 0
	s_add_i32 s72, s72, 2
	s_add_u32 s10, s10, 0x100
	s_addc_u32 s11, s11, 0
	s_cmp_gt_u32 s72, 13
	s_cbranch_scc0 .LBB0_131
	s_branch .Lpeel_g1_exit

.Lpeel_g1_exit:
	s_and_b64 vcc, exec, s[18:19]
	s_cbranch_vccz .LBB0_134
	s_barrier

.LBB0_344:
	s_ashr_i32 s23, s22, 31
	s_lshl_b64 s[24:25], s[22:23], 19
	s_add_u32 s24, s40, s24
	s_addc_u32 s25, s41, s25
	s_and_b64 s[26:27], s[18:19], exec
	s_cselect_b32 s23, s25, s29
	s_cselect_b32 s71, s24, s28
	s_ashr_i32 s21, s20, 31
	s_lshl_b64 s[26:27], s[20:21], 19
	s_add_u32 s26, s42, s26
	s_addc_u32 s27, s43, s27
	s_and_b64 s[34:35], s[18:19], exec
	s_cselect_b32 s21, s27, s31
	s_cselect_b32 s72, s26, s30
	s_add_u32 s73, s71, 0x80
	s_addc_u32 s74, s23, 0
	s_add_u32 s34, s28, 0x40080
	s_addc_u32 s35, s29, 0
	s_add_u32 s75, s30, 0x100
	s_waitcnt lgkmcnt(0)
	v_lshl_add_u64 v[144:145], s[34:35], 0, v[140:141]
	v_lshl_add_u64 v[146:147], s[34:35], 0, v[142:143]
	s_addc_u32 s76, s31, 0
	s_mov_b32 s78, -2
	s_mov_b64 s[30:31], 0
	s_add_u32 s34, s28, s30
	s_addc_u32 s35, s29, s31
	s_add_u32 s38, s34, 0x100
	s_addc_u32 s39, s35, 0
	s_add_u32 s36, s75, s30
	s_addc_u32 s37, s76, s31
	s_add_u32 s34, s34, 0x180
	s_addc_u32 s35, s35, 0
	s_add_i32 s85, 0, 0x10000
	s_add_i32 vcc_lo, 0, 0x14000
	v_add_u32_e32 v0, s85, v152
	ds_read_b128 v[148:151], v0
	ds_read_b128 v[154:157], v0 offset:1024
	ds_read_b128 v[158:161], v0 offset:2048
	ds_read_b128 v[162:165], v0 offset:3072
	v_add_u32_e32 v0, vcc_lo, v152
	ds_read_b128 v[166:169], v0
	ds_read_b128 v[170:173], v0 offset:1024
	ds_read_b128 v[174:177], v0 offset:2048
	ds_read_b128 v[178:181], v0 offset:3072
	s_cmpk_eq_i32 s30, 0x700
	s_cselect_b32 s35, s74, s35
	s_cselect_b32 s34, s73, s34
	s_cselect_b32 s37, s21, s37
	s_cselect_b32 s36, s72, s36
	s_cselect_b32 s39, s23, s39
	s_cselect_b32 s38, s71, s38
	v_lshl_add_u64 v[194:195], v[144:145], 0, s[30:31]
	s_add_i32 m0, s45, 0xc000
	ds_read_b128 v[182:185], v153
	ds_read_b128 v[186:189], v153 offset:1024
	ds_read_b128 v[190:193], v153 offset:2048
	ds_read_b128 v[202:205], v153 offset:3072
	ds_read_b128 v[206:209], v153 offset:4096
	ds_read_b128 v[210:213], v153 offset:5120
	ds_read_b128 v[214:217], v153 offset:6144
	ds_read_b128 v[218:221], v153 offset:7168
	global_load_lds_dwordx4 v[194:195], off
	v_lshl_add_u64 v[194:195], v[146:147], 0, s[30:31]
	s_add_i32 m0, s45, 0xe000
	s_nop 0
	global_load_lds_dwordx4 v[194:195], off
	s_waitcnt vmcnt(8)
	s_waitcnt lgkmcnt(0)
	s_setprio 1
	s_barrier
	v_mfma_f32_16x16x32_bf16 v[126:129], v[148:151], v[182:185], 0
	v_mfma_f32_16x16x32_bf16 v[122:125], v[158:161], v[182:185], 0
	v_mfma_f32_16x16x32_bf16 v[110:113], v[148:151], v[190:193], 0
	v_mfma_f32_16x16x32_bf16 v[106:109], v[158:161], v[190:193], 0
	v_mfma_f32_16x16x32_bf16 v[94:97], v[148:151], v[206:209], 0
	v_mfma_f32_16x16x32_bf16 v[90:93], v[158:161], v[206:209], 0
	v_mfma_f32_16x16x32_bf16 v[78:81], v[148:151], v[214:217], 0
	v_mfma_f32_16x16x32_bf16 v[74:77], v[158:161], v[214:217], 0
	v_mfma_f32_16x16x32_bf16 v[126:129], v[154:157], v[186:189], v[126:129]
	v_mfma_f32_16x16x32_bf16 v[122:125], v[162:165], v[186:189], v[122:125]
	v_mfma_f32_16x16x32_bf16 v[110:113], v[154:157], v[202:205], v[110:113]
	v_mfma_f32_16x16x32_bf16 v[106:109], v[162:165], v[202:205], v[106:109]
	v_mfma_f32_16x16x32_bf16 v[94:97], v[154:157], v[210:213], v[94:97]
	v_mfma_f32_16x16x32_bf16 v[90:93], v[162:165], v[210:213], v[90:93]
	v_mfma_f32_16x16x32_bf16 v[78:81], v[154:157], v[218:221], v[78:81]
	v_mfma_f32_16x16x32_bf16 v[74:77], v[162:165], v[218:221], v[74:77]
	v_mfma_f32_16x16x32_bf16 v[118:121], v[166:169], v[182:185], 0
	v_mfma_f32_16x16x32_bf16 v[114:117], v[174:177], v[182:185], 0
	v_mfma_f32_16x16x32_bf16 v[102:105], v[166:169], v[190:193], 0
	v_mfma_f32_16x16x32_bf16 v[98:101], v[174:177], v[190:193], 0
	v_mfma_f32_16x16x32_bf16 v[86:89], v[166:169], v[206:209], 0
	v_mfma_f32_16x16x32_bf16 v[82:85], v[174:177], v[206:209], 0
	v_mfma_f32_16x16x32_bf16 v[70:73], v[166:169], v[214:217], 0
	v_mfma_f32_16x16x32_bf16 v[66:69], v[174:177], v[214:217], 0
	v_mfma_f32_16x16x32_bf16 v[118:121], v[170:173], v[186:189], v[118:121]
	v_mfma_f32_16x16x32_bf16 v[114:117], v[178:181], v[186:189], v[114:117]
	v_mfma_f32_16x16x32_bf16 v[102:105], v[170:173], v[202:205], v[102:105]
	v_mfma_f32_16x16x32_bf16 v[98:101], v[178:181], v[202:205], v[98:101]
	v_mfma_f32_16x16x32_bf16 v[86:89], v[170:173], v[210:213], v[86:89]
	v_mfma_f32_16x16x32_bf16 v[82:85], v[178:181], v[210:213], v[82:85]
	v_mfma_f32_16x16x32_bf16 v[70:73], v[170:173], v[218:221], v[70:73]
	v_mfma_f32_16x16x32_bf16 v[66:69], v[178:181], v[218:221], v[66:69]
	s_barrier
	s_setprio 0
	s_add_i32 s85, s85, s44
	v_lshl_add_u64 v[194:195], s[36:37], 0, v[134:135]
	s_mov_b32 m0, s85
	ds_read_b128 v[182:185], v153 offset:16384
	ds_read_b128 v[186:189], v153 offset:17408
	ds_read_b128 v[190:193], v153 offset:18432
	ds_read_b128 v[202:205], v153 offset:19456
	ds_read_b128 v[206:209], v153 offset:20480
	ds_read_b128 v[210:213], v153 offset:21504
	ds_read_b128 v[214:217], v153 offset:22528
	ds_read_b128 v[218:221], v153 offset:23552
	global_load_lds_dwordx4 v[194:195], off
	s_add_i32 m0, s85, 0x2000
	s_add_u32 s86, s36, 0x40000
	v_lshl_add_u64 v[198:199], s[36:37], 0, v[130:131]
	s_addc_u32 s87, s37, 0
	s_add_i32 s85, vcc_lo, s44
	global_load_lds_dwordx4 v[198:199], off
	v_lshl_add_u64 v[222:223], s[86:87], 0, v[134:135]
	s_mov_b32 m0, s85
	s_nop 0
	global_load_lds_dwordx4 v[222:223], off
	v_lshl_add_u64 v[222:223], s[86:87], 0, v[130:131]
	s_add_i32 m0, s85, 0x2000
	s_nop 0
	global_load_lds_dwordx4 v[222:223], off
	v_lshl_add_u64 v[222:223], s[38:39], 0, v[136:137]
	s_mov_b32 m0, s45
	s_nop 0
	global_load_lds_dwordx4 v[222:223], off
	v_lshl_add_u64 v[222:223], s[38:39], 0, v[132:133]
	s_mov_b32 m0, s51
	s_nop 0
	global_load_lds_dwordx4 v[222:223], off
	s_waitcnt vmcnt(8)
	s_waitcnt lgkmcnt(0)
	s_setprio 1
	s_barrier
	v_mfma_f32_16x16x32_bf16 v[62:65], v[148:151], v[182:185], 0
	v_mfma_f32_16x16x32_bf16 v[58:61], v[158:161], v[182:185], 0
	v_mfma_f32_16x16x32_bf16 v[46:49], v[148:151], v[190:193], 0
	v_mfma_f32_16x16x32_bf16 v[42:45], v[158:161], v[190:193], 0
	v_mfma_f32_16x16x32_bf16 v[30:33], v[148:151], v[206:209], 0
	v_mfma_f32_16x16x32_bf16 v[26:29], v[158:161], v[206:209], 0
	v_mfma_f32_16x16x32_bf16 v[14:17], v[148:151], v[214:217], 0
	v_mfma_f32_16x16x32_bf16 v[10:13], v[158:161], v[214:217], 0
	v_mfma_f32_16x16x32_bf16 v[62:65], v[154:157], v[186:189], v[62:65]
	v_mfma_f32_16x16x32_bf16 v[58:61], v[162:165], v[186:189], v[58:61]
	v_mfma_f32_16x16x32_bf16 v[46:49], v[154:157], v[202:205], v[46:49]
	v_mfma_f32_16x16x32_bf16 v[42:45], v[162:165], v[202:205], v[42:45]
	v_mfma_f32_16x16x32_bf16 v[30:33], v[154:157], v[210:213], v[30:33]
	v_mfma_f32_16x16x32_bf16 v[26:29], v[162:165], v[210:213], v[26:29]
	v_mfma_f32_16x16x32_bf16 v[14:17], v[154:157], v[218:221], v[14:17]
	v_mfma_f32_16x16x32_bf16 v[10:13], v[162:165], v[218:221], v[10:13]
	v_mfma_f32_16x16x32_bf16 v[54:57], v[166:169], v[182:185], 0
	v_mfma_f32_16x16x32_bf16 v[50:53], v[174:177], v[182:185], 0
	v_mfma_f32_16x16x32_bf16 v[38:41], v[166:169], v[190:193], 0
	v_mfma_f32_16x16x32_bf16 v[34:37], v[174:177], v[190:193], 0
	v_mfma_f32_16x16x32_bf16 v[22:25], v[166:169], v[206:209], 0
	v_mfma_f32_16x16x32_bf16 v[18:21], v[174:177], v[206:209], 0
	v_mfma_f32_16x16x32_bf16 v[6:9], v[166:169], v[214:217], 0
	v_mfma_f32_16x16x32_bf16 v[2:5], v[174:177], v[214:217], 0
	v_mfma_f32_16x16x32_bf16 v[54:57], v[170:173], v[186:189], v[54:57]
	v_mfma_f32_16x16x32_bf16 v[50:53], v[178:181], v[186:189], v[50:53]
	v_mfma_f32_16x16x32_bf16 v[38:41], v[170:173], v[202:205], v[38:41]
	v_mfma_f32_16x16x32_bf16 v[34:37], v[178:181], v[202:205], v[34:37]
	v_mfma_f32_16x16x32_bf16 v[22:25], v[170:173], v[210:213], v[22:25]
	v_mfma_f32_16x16x32_bf16 v[18:21], v[178:181], v[210:213], v[18:21]
	v_mfma_f32_16x16x32_bf16 v[6:9], v[170:173], v[218:221], v[6:9]
	v_mfma_f32_16x16x32_bf16 v[2:5], v[178:181], v[218:221], v[2:5]
	s_barrier
	s_setprio 0
	s_add_i32 s85, 0, 0x18000
	v_add_u32_e32 v0, s85, v152
	s_add_i32 s86, 0, 0x1c000
	ds_read_b128 v[148:151], v0
	ds_read_b128 v[154:157], v0 offset:1024
	ds_read_b128 v[158:161], v0 offset:2048
	ds_read_b128 v[162:165], v0 offset:3072
	v_add_u32_e32 v0, s86, v152
	ds_read_b128 v[166:169], v0
	ds_read_b128 v[170:173], v0 offset:1024
	ds_read_b128 v[174:177], v0 offset:2048
	ds_read_b128 v[178:181], v0 offset:3072
	s_add_u32 s38, s38, 0x40000
	s_addc_u32 s39, s39, 0
	s_mov_b32 m0, s55
	v_lshl_add_u64 v[222:223], s[38:39], 0, v[136:137]
	ds_read_b128 v[182:185], v153 offset:32768
	ds_read_b128 v[186:189], v153 offset:33792
	ds_read_b128 v[190:193], v153 offset:34816
	ds_read_b128 v[202:205], v153 offset:35840
	ds_read_b128 v[206:209], v153 offset:36864
	ds_read_b128 v[210:213], v153 offset:37888
	ds_read_b128 v[214:217], v153 offset:38912
	ds_read_b128 v[218:221], v153 offset:39936
	global_load_lds_dwordx4 v[222:223], off
	v_lshl_add_u64 v[222:223], s[38:39], 0, v[132:133]
	s_mov_b32 m0, s56
	s_nop 0
	global_load_lds_dwordx4 v[222:223], off
	s_waitcnt vmcnt(8)
	s_waitcnt lgkmcnt(0)
	s_setprio 1
	s_barrier
	v_mfma_f32_16x16x32_bf16 v[126:129], v[148:151], v[182:185], v[126:129]
	v_mfma_f32_16x16x32_bf16 v[122:125], v[158:161], v[182:185], v[122:125]
	v_mfma_f32_16x16x32_bf16 v[110:113], v[148:151], v[190:193], v[110:113]
	v_mfma_f32_16x16x32_bf16 v[106:109], v[158:161], v[190:193], v[106:109]
	v_mfma_f32_16x16x32_bf16 v[94:97], v[148:151], v[206:209], v[94:97]
	v_mfma_f32_16x16x32_bf16 v[90:93], v[158:161], v[206:209], v[90:93]
	v_mfma_f32_16x16x32_bf16 v[78:81], v[148:151], v[214:217], v[78:81]
	v_mfma_f32_16x16x32_bf16 v[74:77], v[158:161], v[214:217], v[74:77]
	v_mfma_f32_16x16x32_bf16 v[126:129], v[154:157], v[186:189], v[126:129]
	v_mfma_f32_16x16x32_bf16 v[122:125], v[162:165], v[186:189], v[122:125]
	v_mfma_f32_16x16x32_bf16 v[110:113], v[154:157], v[202:205], v[110:113]
	v_mfma_f32_16x16x32_bf16 v[106:109], v[162:165], v[202:205], v[106:109]
	v_mfma_f32_16x16x32_bf16 v[94:97], v[154:157], v[210:213], v[94:97]
	v_mfma_f32_16x16x32_bf16 v[90:93], v[162:165], v[210:213], v[90:93]
	v_mfma_f32_16x16x32_bf16 v[78:81], v[154:157], v[218:221], v[78:81]
	v_mfma_f32_16x16x32_bf16 v[74:77], v[162:165], v[218:221], v[74:77]
	v_mfma_f32_16x16x32_bf16 v[118:121], v[166:169], v[182:185], v[118:121]
	v_mfma_f32_16x16x32_bf16 v[114:117], v[174:177], v[182:185], v[114:117]
	v_mfma_f32_16x16x32_bf16 v[102:105], v[166:169], v[190:193], v[102:105]
	v_mfma_f32_16x16x32_bf16 v[98:101], v[174:177], v[190:193], v[98:101]
	v_mfma_f32_16x16x32_bf16 v[86:89], v[166:169], v[206:209], v[86:89]
	v_mfma_f32_16x16x32_bf16 v[82:85], v[174:177], v[206:209], v[82:85]
	v_mfma_f32_16x16x32_bf16 v[70:73], v[166:169], v[214:217], v[70:73]
	v_mfma_f32_16x16x32_bf16 v[66:69], v[174:177], v[214:217], v[66:69]
	v_mfma_f32_16x16x32_bf16 v[118:121], v[170:173], v[186:189], v[118:121]
	v_mfma_f32_16x16x32_bf16 v[114:117], v[178:181], v[186:189], v[114:117]
	v_mfma_f32_16x16x32_bf16 v[102:105], v[170:173], v[202:205], v[102:105]
	v_mfma_f32_16x16x32_bf16 v[98:101], v[178:181], v[202:205], v[98:101]
	v_mfma_f32_16x16x32_bf16 v[86:89], v[170:173], v[210:213], v[86:89]
	v_mfma_f32_16x16x32_bf16 v[82:85], v[178:181], v[210:213], v[82:85]
	v_mfma_f32_16x16x32_bf16 v[70:73], v[170:173], v[218:221], v[70:73]
	v_mfma_f32_16x16x32_bf16 v[66:69], v[178:181], v[218:221], v[66:69]
	s_barrier
	s_setprio 0
	s_add_i32 s38, s85, s44
	v_lshl_add_u64 v[194:195], v[194:195], 0, s[90:91]
	s_mov_b32 m0, s38
	ds_read_b128 v[182:185], v153 offset:49152
	ds_read_b128 v[186:189], v153 offset:50176
	ds_read_b128 v[190:193], v153 offset:51200
	ds_read_b128 v[202:205], v153 offset:52224
	ds_read_b128 v[206:209], v153 offset:53248
	ds_read_b128 v[210:213], v153 offset:54272
	ds_read_b128 v[214:217], v153 offset:55296
	ds_read_b128 v[218:221], v153 offset:56320
	global_load_lds_dwordx4 v[194:195], off
	s_add_i32 m0, s38, 0x2000
	s_add_u32 s36, s36, 0x40080
	v_lshl_add_u64 v[194:195], v[198:199], 0, s[90:91]
	s_addc_u32 s37, s37, 0
	s_add_i32 s38, s86, s44
	global_load_lds_dwordx4 v[194:195], off
	v_lshl_add_u64 v[194:195], s[36:37], 0, v[134:135]
	s_mov_b32 m0, s38
	s_nop 0
	global_load_lds_dwordx4 v[194:195], off
	v_lshl_add_u64 v[194:195], s[36:37], 0, v[130:131]
	s_add_i32 m0, s38, 0x2000
	s_nop 0
	global_load_lds_dwordx4 v[194:195], off
	v_lshl_add_u64 v[194:195], s[34:35], 0, v[136:137]
	s_mov_b32 m0, s58
	s_nop 0
	global_load_lds_dwordx4 v[194:195], off
	v_lshl_add_u64 v[194:195], s[34:35], 0, v[132:133]
	s_mov_b32 m0, s59
	s_nop 0
	global_load_lds_dwordx4 v[194:195], off
	s_waitcnt vmcnt(8)
	s_waitcnt lgkmcnt(0)
	s_setprio 1
	s_barrier
	v_mfma_f32_16x16x32_bf16 v[62:65], v[148:151], v[182:185], v[62:65]
	v_mfma_f32_16x16x32_bf16 v[58:61], v[158:161], v[182:185], v[58:61]
	v_mfma_f32_16x16x32_bf16 v[46:49], v[148:151], v[190:193], v[46:49]
	v_mfma_f32_16x16x32_bf16 v[42:45], v[158:161], v[190:193], v[42:45]
	v_mfma_f32_16x16x32_bf16 v[30:33], v[148:151], v[206:209], v[30:33]
	v_mfma_f32_16x16x32_bf16 v[26:29], v[158:161], v[206:209], v[26:29]
	v_mfma_f32_16x16x32_bf16 v[14:17], v[148:151], v[214:217], v[14:17]
	v_mfma_f32_16x16x32_bf16 v[10:13], v[158:161], v[214:217], v[10:13]
	v_mfma_f32_16x16x32_bf16 v[62:65], v[154:157], v[186:189], v[62:65]
	v_mfma_f32_16x16x32_bf16 v[58:61], v[162:165], v[186:189], v[58:61]
	v_mfma_f32_16x16x32_bf16 v[46:49], v[154:157], v[202:205], v[46:49]
	v_mfma_f32_16x16x32_bf16 v[42:45], v[162:165], v[202:205], v[42:45]
	v_mfma_f32_16x16x32_bf16 v[30:33], v[154:157], v[210:213], v[30:33]
	v_mfma_f32_16x16x32_bf16 v[26:29], v[162:165], v[210:213], v[26:29]
	v_mfma_f32_16x16x32_bf16 v[14:17], v[154:157], v[218:221], v[14:17]
	v_mfma_f32_16x16x32_bf16 v[10:13], v[162:165], v[218:221], v[10:13]
	v_mfma_f32_16x16x32_bf16 v[54:57], v[166:169], v[182:185], v[54:57]
	v_mfma_f32_16x16x32_bf16 v[50:53], v[174:177], v[182:185], v[50:53]
	v_mfma_f32_16x16x32_bf16 v[38:41], v[166:169], v[190:193], v[38:41]
	v_mfma_f32_16x16x32_bf16 v[34:37], v[174:177], v[190:193], v[34:37]
	v_mfma_f32_16x16x32_bf16 v[22:25], v[166:169], v[206:209], v[22:25]
	v_mfma_f32_16x16x32_bf16 v[18:21], v[174:177], v[206:209], v[18:21]
	v_mfma_f32_16x16x32_bf16 v[6:9], v[166:169], v[214:217], v[6:9]
	v_mfma_f32_16x16x32_bf16 v[2:5], v[174:177], v[214:217], v[2:5]
	v_mfma_f32_16x16x32_bf16 v[54:57], v[170:173], v[186:189], v[54:57]
	v_mfma_f32_16x16x32_bf16 v[50:53], v[178:181], v[186:189], v[50:53]
	v_mfma_f32_16x16x32_bf16 v[38:41], v[170:173], v[202:205], v[38:41]
	v_mfma_f32_16x16x32_bf16 v[34:37], v[178:181], v[202:205], v[34:37]
	v_mfma_f32_16x16x32_bf16 v[22:25], v[170:173], v[210:213], v[22:25]
	v_mfma_f32_16x16x32_bf16 v[18:21], v[178:181], v[210:213], v[18:21]
	v_mfma_f32_16x16x32_bf16 v[6:9], v[170:173], v[218:221], v[6:9]
	v_mfma_f32_16x16x32_bf16 v[2:5], v[178:181], v[218:221], v[2:5]
	s_barrier
	s_setprio 0
	s_add_i32 s78, s78, 2
	s_add_u32 s30, s30, 0x100
	s_addc_u32 s31, s31, 0
	s_cmp_gt_u32 s78, 13
	s_cbranch_scc0 .LBB0_345
	s_branch .Lpeel_kv_exit

.Lpeel_kv_exit:
	s_and_b64 vcc, exec, s[16:17]
	s_cbranch_vccz .LBB0_348
	s_barrier

.LBB0_674:
	s_ashr_i32 s25, s24, 31
	s_lshl_b64 s[26:27], s[24:25], 19
	s_add_u32 s26, s42, s26
	s_addc_u32 s27, s43, s27
	s_and_b64 s[28:29], s[10:11], exec
	s_cselect_b32 s25, s27, s31
	s_cselect_b32 s73, s26, s30
	s_ashr_i32 s23, s22, 31
	s_lshl_b64 s[28:29], s[22:23], 19
	s_add_u32 s28, s44, s28
	s_addc_u32 s29, s45, s29
	s_and_b64 s[36:37], s[10:11], exec
	s_cselect_b32 s23, s29, s35
	s_cselect_b32 s74, s28, s34
	s_add_u32 s75, s73, 0x80
	s_addc_u32 s76, s25, 0
	s_add_u32 s36, s30, 0x40080
	s_addc_u32 s37, s31, 0
	s_add_u32 s78, s34, 0x100
	s_waitcnt lgkmcnt(0)
	v_lshl_add_u64 v[144:145], s[36:37], 0, v[140:141]
	v_lshl_add_u64 v[146:147], s[36:37], 0, v[142:143]
	s_addc_u32 s85, s35, 0
	s_mov_b32 s86, -2
	s_mov_b64 s[34:35], 0
	s_add_u32 s4, s30, s34
	s_addc_u32 s5, s31, s35
	s_add_u32 s40, s4, 0x100
	s_addc_u32 s41, s5, 0
	s_add_u32 s38, s78, s34
	s_addc_u32 s39, s85, s35
	s_add_u32 s4, s4, 0x180
	s_addc_u32 s5, s5, 0
	s_add_i32 s87, 0, 0x10000
	s_add_i32 s65, 0, 0x14000
	v_add_u32_e32 v0, s87, v148
	ds_read_b128 v[150:153], v0
	ds_read_b128 v[154:157], v0 offset:1024
	ds_read_b128 v[158:161], v0 offset:2048
	ds_read_b128 v[162:165], v0 offset:3072
	v_add_u32_e32 v0, s65, v148
	ds_read_b128 v[166:169], v0
	ds_read_b128 v[170:173], v0 offset:1024
	ds_read_b128 v[174:177], v0 offset:2048
	ds_read_b128 v[178:181], v0 offset:3072
	s_cmpk_eq_i32 s34, 0x700
	s_cselect_b32 s37, s76, s5
	s_cselect_b32 s36, s75, s4
	s_cselect_b32 s39, s23, s39
	s_cselect_b32 s38, s74, s38
	s_cselect_b32 s41, s25, s41
	s_cselect_b32 s40, s73, s40
	v_lshl_add_u64 v[194:195], v[144:145], 0, s[34:35]
	s_add_i32 m0, s55, 0xc000
	ds_read_b128 v[182:185], v149
	ds_read_b128 v[186:189], v149 offset:1024
	ds_read_b128 v[190:193], v149 offset:2048
	ds_read_b128 v[202:205], v149 offset:3072
	ds_read_b128 v[206:209], v149 offset:4096
	ds_read_b128 v[210:213], v149 offset:5120
	ds_read_b128 v[214:217], v149 offset:6144
	ds_read_b128 v[218:221], v149 offset:7168
	global_load_lds_dwordx4 v[194:195], off
	v_lshl_add_u64 v[194:195], v[146:147], 0, s[34:35]
	s_add_i32 m0, s55, 0xe000
	s_nop 0
	global_load_lds_dwordx4 v[194:195], off
	s_waitcnt vmcnt(8)
	s_waitcnt lgkmcnt(0)
	s_setprio 1
	s_barrier
	v_mfma_f32_16x16x32_bf16 v[126:129], v[150:153], v[182:185], 0
	v_mfma_f32_16x16x32_bf16 v[122:125], v[158:161], v[182:185], 0
	v_mfma_f32_16x16x32_bf16 v[110:113], v[150:153], v[190:193], 0
	v_mfma_f32_16x16x32_bf16 v[106:109], v[158:161], v[190:193], 0
	v_mfma_f32_16x16x32_bf16 v[94:97], v[150:153], v[206:209], 0
	v_mfma_f32_16x16x32_bf16 v[90:93], v[158:161], v[206:209], 0
	v_mfma_f32_16x16x32_bf16 v[78:81], v[150:153], v[214:217], 0
	v_mfma_f32_16x16x32_bf16 v[74:77], v[158:161], v[214:217], 0
	v_mfma_f32_16x16x32_bf16 v[126:129], v[154:157], v[186:189], v[126:129]
	v_mfma_f32_16x16x32_bf16 v[122:125], v[162:165], v[186:189], v[122:125]
	v_mfma_f32_16x16x32_bf16 v[110:113], v[154:157], v[202:205], v[110:113]
	v_mfma_f32_16x16x32_bf16 v[106:109], v[162:165], v[202:205], v[106:109]
	v_mfma_f32_16x16x32_bf16 v[94:97], v[154:157], v[210:213], v[94:97]
	v_mfma_f32_16x16x32_bf16 v[90:93], v[162:165], v[210:213], v[90:93]
	v_mfma_f32_16x16x32_bf16 v[78:81], v[154:157], v[218:221], v[78:81]
	v_mfma_f32_16x16x32_bf16 v[74:77], v[162:165], v[218:221], v[74:77]
	v_mfma_f32_16x16x32_bf16 v[118:121], v[166:169], v[182:185], 0
	v_mfma_f32_16x16x32_bf16 v[114:117], v[174:177], v[182:185], 0
	v_mfma_f32_16x16x32_bf16 v[102:105], v[166:169], v[190:193], 0
	v_mfma_f32_16x16x32_bf16 v[98:101], v[174:177], v[190:193], 0
	v_mfma_f32_16x16x32_bf16 v[86:89], v[166:169], v[206:209], 0
	v_mfma_f32_16x16x32_bf16 v[82:85], v[174:177], v[206:209], 0
	v_mfma_f32_16x16x32_bf16 v[70:73], v[166:169], v[214:217], 0
	v_mfma_f32_16x16x32_bf16 v[66:69], v[174:177], v[214:217], 0
	v_mfma_f32_16x16x32_bf16 v[118:121], v[170:173], v[186:189], v[118:121]
	v_mfma_f32_16x16x32_bf16 v[114:117], v[178:181], v[186:189], v[114:117]
	v_mfma_f32_16x16x32_bf16 v[102:105], v[170:173], v[202:205], v[102:105]
	v_mfma_f32_16x16x32_bf16 v[98:101], v[178:181], v[202:205], v[98:101]
	v_mfma_f32_16x16x32_bf16 v[86:89], v[170:173], v[210:213], v[86:89]
	v_mfma_f32_16x16x32_bf16 v[82:85], v[178:181], v[210:213], v[82:85]
	v_mfma_f32_16x16x32_bf16 v[70:73], v[170:173], v[218:221], v[70:73]
	v_mfma_f32_16x16x32_bf16 v[66:69], v[178:181], v[218:221], v[66:69]
	s_barrier
	s_setprio 0
	s_add_i32 s4, s87, s51
	v_lshl_add_u64 v[194:195], s[38:39], 0, v[134:135]
	s_mov_b32 m0, s4
	ds_read_b128 v[182:185], v149 offset:16384
	ds_read_b128 v[186:189], v149 offset:17408
	ds_read_b128 v[190:193], v149 offset:18432
	ds_read_b128 v[202:205], v149 offset:19456
	ds_read_b128 v[206:209], v149 offset:20480
	ds_read_b128 v[210:213], v149 offset:21504
	ds_read_b128 v[214:217], v149 offset:22528
	ds_read_b128 v[218:221], v149 offset:23552
	global_load_lds_dwordx4 v[194:195], off
	s_add_i32 m0, s4, 0x2000
	s_add_u32 vcc_lo, s38, 0x40000
	v_lshl_add_u64 v[198:199], s[38:39], 0, v[130:131]
	s_addc_u32 vcc_hi, s39, 0
	s_add_i32 s4, s65, s51
	global_load_lds_dwordx4 v[198:199], off
	v_lshl_add_u64 v[222:223], vcc, 0, v[134:135]
	s_mov_b32 m0, s4
	s_nop 0
	global_load_lds_dwordx4 v[222:223], off
	v_lshl_add_u64 v[222:223], vcc, 0, v[130:131]
	s_add_i32 m0, s4, 0x2000
	s_nop 0
	global_load_lds_dwordx4 v[222:223], off
	v_lshl_add_u64 v[222:223], s[40:41], 0, v[136:137]
	s_mov_b32 m0, s55
	s_nop 0
	global_load_lds_dwordx4 v[222:223], off
	v_lshl_add_u64 v[222:223], s[40:41], 0, v[132:133]
	s_mov_b32 m0, s56
	s_nop 0
	global_load_lds_dwordx4 v[222:223], off
	s_waitcnt vmcnt(8)
	s_waitcnt lgkmcnt(0)
	s_setprio 1
	s_barrier
	v_mfma_f32_16x16x32_bf16 v[62:65], v[150:153], v[182:185], 0
	v_mfma_f32_16x16x32_bf16 v[58:61], v[158:161], v[182:185], 0
	v_mfma_f32_16x16x32_bf16 v[46:49], v[150:153], v[190:193], 0
	v_mfma_f32_16x16x32_bf16 v[42:45], v[158:161], v[190:193], 0
	v_mfma_f32_16x16x32_bf16 v[30:33], v[150:153], v[206:209], 0
	v_mfma_f32_16x16x32_bf16 v[26:29], v[158:161], v[206:209], 0
	v_mfma_f32_16x16x32_bf16 v[14:17], v[150:153], v[214:217], 0
	v_mfma_f32_16x16x32_bf16 v[10:13], v[158:161], v[214:217], 0
	v_mfma_f32_16x16x32_bf16 v[62:65], v[154:157], v[186:189], v[62:65]
	v_mfma_f32_16x16x32_bf16 v[58:61], v[162:165], v[186:189], v[58:61]
	v_mfma_f32_16x16x32_bf16 v[46:49], v[154:157], v[202:205], v[46:49]
	v_mfma_f32_16x16x32_bf16 v[42:45], v[162:165], v[202:205], v[42:45]
	v_mfma_f32_16x16x32_bf16 v[30:33], v[154:157], v[210:213], v[30:33]
	v_mfma_f32_16x16x32_bf16 v[26:29], v[162:165], v[210:213], v[26:29]
	v_mfma_f32_16x16x32_bf16 v[14:17], v[154:157], v[218:221], v[14:17]
	v_mfma_f32_16x16x32_bf16 v[10:13], v[162:165], v[218:221], v[10:13]
	v_mfma_f32_16x16x32_bf16 v[54:57], v[166:169], v[182:185], 0
	v_mfma_f32_16x16x32_bf16 v[50:53], v[174:177], v[182:185], 0
	v_mfma_f32_16x16x32_bf16 v[38:41], v[166:169], v[190:193], 0
	v_mfma_f32_16x16x32_bf16 v[34:37], v[174:177], v[190:193], 0
	v_mfma_f32_16x16x32_bf16 v[22:25], v[166:169], v[206:209], 0
	v_mfma_f32_16x16x32_bf16 v[18:21], v[174:177], v[206:209], 0
	v_mfma_f32_16x16x32_bf16 v[6:9], v[166:169], v[214:217], 0
	v_mfma_f32_16x16x32_bf16 v[2:5], v[174:177], v[214:217], 0
	v_mfma_f32_16x16x32_bf16 v[54:57], v[170:173], v[186:189], v[54:57]
	v_mfma_f32_16x16x32_bf16 v[50:53], v[178:181], v[186:189], v[50:53]
	v_mfma_f32_16x16x32_bf16 v[38:41], v[170:173], v[202:205], v[38:41]
	v_mfma_f32_16x16x32_bf16 v[34:37], v[178:181], v[202:205], v[34:37]
	v_mfma_f32_16x16x32_bf16 v[22:25], v[170:173], v[210:213], v[22:25]
	v_mfma_f32_16x16x32_bf16 v[18:21], v[178:181], v[210:213], v[18:21]
	v_mfma_f32_16x16x32_bf16 v[6:9], v[170:173], v[218:221], v[6:9]
	v_mfma_f32_16x16x32_bf16 v[2:5], v[178:181], v[218:221], v[2:5]
	s_barrier
	s_setprio 0
	s_add_i32 s4, 0, 0x18000
	v_add_u32_e32 v0, s4, v148
	s_add_i32 s5, 0, 0x1c000
	ds_read_b128 v[150:153], v0
	ds_read_b128 v[154:157], v0 offset:1024
	ds_read_b128 v[158:161], v0 offset:2048
	ds_read_b128 v[162:165], v0 offset:3072
	v_add_u32_e32 v0, s5, v148
	ds_read_b128 v[166:169], v0
	ds_read_b128 v[170:173], v0 offset:1024
	ds_read_b128 v[174:177], v0 offset:2048
	ds_read_b128 v[178:181], v0 offset:3072
	s_add_u32 s40, s40, 0x40000
	s_addc_u32 s41, s41, 0
	s_mov_b32 m0, s57
	v_lshl_add_u64 v[222:223], s[40:41], 0, v[136:137]
	ds_read_b128 v[182:185], v149 offset:32768
	ds_read_b128 v[186:189], v149 offset:33792
	ds_read_b128 v[190:193], v149 offset:34816
	ds_read_b128 v[202:205], v149 offset:35840
	ds_read_b128 v[206:209], v149 offset:36864
	ds_read_b128 v[210:213], v149 offset:37888
	ds_read_b128 v[214:217], v149 offset:38912
	ds_read_b128 v[218:221], v149 offset:39936
	global_load_lds_dwordx4 v[222:223], off
	v_lshl_add_u64 v[222:223], s[40:41], 0, v[132:133]
	s_mov_b32 m0, s58
	s_nop 0
	global_load_lds_dwordx4 v[222:223], off
	s_waitcnt vmcnt(8)
	s_waitcnt lgkmcnt(0)
	s_setprio 1
	s_barrier
	v_mfma_f32_16x16x32_bf16 v[126:129], v[150:153], v[182:185], v[126:129]
	v_mfma_f32_16x16x32_bf16 v[122:125], v[158:161], v[182:185], v[122:125]
	v_mfma_f32_16x16x32_bf16 v[110:113], v[150:153], v[190:193], v[110:113]
	v_mfma_f32_16x16x32_bf16 v[106:109], v[158:161], v[190:193], v[106:109]
	v_mfma_f32_16x16x32_bf16 v[94:97], v[150:153], v[206:209], v[94:97]
	v_mfma_f32_16x16x32_bf16 v[90:93], v[158:161], v[206:209], v[90:93]
	v_mfma_f32_16x16x32_bf16 v[78:81], v[150:153], v[214:217], v[78:81]
	v_mfma_f32_16x16x32_bf16 v[74:77], v[158:161], v[214:217], v[74:77]
	v_mfma_f32_16x16x32_bf16 v[126:129], v[154:157], v[186:189], v[126:129]
	v_mfma_f32_16x16x32_bf16 v[122:125], v[162:165], v[186:189], v[122:125]
	v_mfma_f32_16x16x32_bf16 v[110:113], v[154:157], v[202:205], v[110:113]
	v_mfma_f32_16x16x32_bf16 v[106:109], v[162:165], v[202:205], v[106:109]
	v_mfma_f32_16x16x32_bf16 v[94:97], v[154:157], v[210:213], v[94:97]
	v_mfma_f32_16x16x32_bf16 v[90:93], v[162:165], v[210:213], v[90:93]
	v_mfma_f32_16x16x32_bf16 v[78:81], v[154:157], v[218:221], v[78:81]
	v_mfma_f32_16x16x32_bf16 v[74:77], v[162:165], v[218:221], v[74:77]
	v_mfma_f32_16x16x32_bf16 v[118:121], v[166:169], v[182:185], v[118:121]
	v_mfma_f32_16x16x32_bf16 v[114:117], v[174:177], v[182:185], v[114:117]
	v_mfma_f32_16x16x32_bf16 v[102:105], v[166:169], v[190:193], v[102:105]
	v_mfma_f32_16x16x32_bf16 v[98:101], v[174:177], v[190:193], v[98:101]
	v_mfma_f32_16x16x32_bf16 v[86:89], v[166:169], v[206:209], v[86:89]
	v_mfma_f32_16x16x32_bf16 v[82:85], v[174:177], v[206:209], v[82:85]
	v_mfma_f32_16x16x32_bf16 v[70:73], v[166:169], v[214:217], v[70:73]
	v_mfma_f32_16x16x32_bf16 v[66:69], v[174:177], v[214:217], v[66:69]
	v_mfma_f32_16x16x32_bf16 v[118:121], v[170:173], v[186:189], v[118:121]
	v_mfma_f32_16x16x32_bf16 v[114:117], v[178:181], v[186:189], v[114:117]
	v_mfma_f32_16x16x32_bf16 v[102:105], v[170:173], v[202:205], v[102:105]
	v_mfma_f32_16x16x32_bf16 v[98:101], v[178:181], v[202:205], v[98:101]
	v_mfma_f32_16x16x32_bf16 v[86:89], v[170:173], v[210:213], v[86:89]
	v_mfma_f32_16x16x32_bf16 v[82:85], v[178:181], v[210:213], v[82:85]
	v_mfma_f32_16x16x32_bf16 v[70:73], v[170:173], v[218:221], v[70:73]
	v_mfma_f32_16x16x32_bf16 v[66:69], v[178:181], v[218:221], v[66:69]
	s_barrier
	s_setprio 0
	s_add_i32 s4, s4, s51
	v_lshl_add_u64 v[194:195], v[194:195], 0, s[90:91]
	s_mov_b32 m0, s4
	ds_read_b128 v[182:185], v149 offset:49152
	ds_read_b128 v[186:189], v149 offset:50176
	ds_read_b128 v[190:193], v149 offset:51200
	ds_read_b128 v[202:205], v149 offset:52224
	ds_read_b128 v[206:209], v149 offset:53248
	ds_read_b128 v[210:213], v149 offset:54272
	ds_read_b128 v[214:217], v149 offset:55296
	ds_read_b128 v[218:221], v149 offset:56320
	global_load_lds_dwordx4 v[194:195], off
	s_add_i32 m0, s4, 0x2000
	s_add_u32 s38, s38, 0x40080
	v_lshl_add_u64 v[194:195], v[198:199], 0, s[90:91]
	s_addc_u32 s39, s39, 0
	s_add_i32 s4, s5, s51
	global_load_lds_dwordx4 v[194:195], off
	v_lshl_add_u64 v[194:195], s[38:39], 0, v[134:135]
	s_mov_b32 m0, s4
	s_nop 0
	global_load_lds_dwordx4 v[194:195], off
	v_lshl_add_u64 v[194:195], s[38:39], 0, v[130:131]
	s_add_i32 m0, s4, 0x2000
	s_nop 0
	global_load_lds_dwordx4 v[194:195], off
	v_lshl_add_u64 v[194:195], s[36:37], 0, v[136:137]
	s_mov_b32 m0, s68
	s_nop 0
	global_load_lds_dwordx4 v[194:195], off
	v_lshl_add_u64 v[194:195], s[36:37], 0, v[132:133]
	s_mov_b32 m0, s69
	s_nop 0
	global_load_lds_dwordx4 v[194:195], off
	s_waitcnt vmcnt(8)
	s_waitcnt lgkmcnt(0)
	s_setprio 1
	s_barrier
	v_mfma_f32_16x16x32_bf16 v[62:65], v[150:153], v[182:185], v[62:65]
	v_mfma_f32_16x16x32_bf16 v[58:61], v[158:161], v[182:185], v[58:61]
	v_mfma_f32_16x16x32_bf16 v[46:49], v[150:153], v[190:193], v[46:49]
	v_mfma_f32_16x16x32_bf16 v[42:45], v[158:161], v[190:193], v[42:45]
	v_mfma_f32_16x16x32_bf16 v[30:33], v[150:153], v[206:209], v[30:33]
	v_mfma_f32_16x16x32_bf16 v[26:29], v[158:161], v[206:209], v[26:29]
	v_mfma_f32_16x16x32_bf16 v[14:17], v[150:153], v[214:217], v[14:17]
	v_mfma_f32_16x16x32_bf16 v[10:13], v[158:161], v[214:217], v[10:13]
	v_mfma_f32_16x16x32_bf16 v[62:65], v[154:157], v[186:189], v[62:65]
	v_mfma_f32_16x16x32_bf16 v[58:61], v[162:165], v[186:189], v[58:61]
	v_mfma_f32_16x16x32_bf16 v[46:49], v[154:157], v[202:205], v[46:49]
	v_mfma_f32_16x16x32_bf16 v[42:45], v[162:165], v[202:205], v[42:45]
	v_mfma_f32_16x16x32_bf16 v[30:33], v[154:157], v[210:213], v[30:33]
	v_mfma_f32_16x16x32_bf16 v[26:29], v[162:165], v[210:213], v[26:29]
	v_mfma_f32_16x16x32_bf16 v[14:17], v[154:157], v[218:221], v[14:17]
	v_mfma_f32_16x16x32_bf16 v[10:13], v[162:165], v[218:221], v[10:13]
	v_mfma_f32_16x16x32_bf16 v[54:57], v[166:169], v[182:185], v[54:57]
	v_mfma_f32_16x16x32_bf16 v[50:53], v[174:177], v[182:185], v[50:53]
	v_mfma_f32_16x16x32_bf16 v[38:41], v[166:169], v[190:193], v[38:41]
	v_mfma_f32_16x16x32_bf16 v[34:37], v[174:177], v[190:193], v[34:37]
	v_mfma_f32_16x16x32_bf16 v[22:25], v[166:169], v[206:209], v[22:25]
	v_mfma_f32_16x16x32_bf16 v[18:21], v[174:177], v[206:209], v[18:21]
	v_mfma_f32_16x16x32_bf16 v[6:9], v[166:169], v[214:217], v[6:9]
	v_mfma_f32_16x16x32_bf16 v[2:5], v[174:177], v[214:217], v[2:5]
	v_mfma_f32_16x16x32_bf16 v[54:57], v[170:173], v[186:189], v[54:57]
	v_mfma_f32_16x16x32_bf16 v[50:53], v[178:181], v[186:189], v[50:53]
	v_mfma_f32_16x16x32_bf16 v[38:41], v[170:173], v[202:205], v[38:41]
	v_mfma_f32_16x16x32_bf16 v[34:37], v[178:181], v[202:205], v[34:37]
	v_mfma_f32_16x16x32_bf16 v[22:25], v[170:173], v[210:213], v[22:25]
	v_mfma_f32_16x16x32_bf16 v[18:21], v[178:181], v[210:213], v[18:21]
	v_mfma_f32_16x16x32_bf16 v[6:9], v[170:173], v[218:221], v[6:9]
	v_mfma_f32_16x16x32_bf16 v[2:5], v[178:181], v[218:221], v[2:5]
	s_barrier
	s_setprio 0
	s_add_i32 s86, s86, 2
	s_add_u32 s34, s34, 0x100
	s_addc_u32 s35, s35, 0
	s_cmp_gt_u32 s86, 13
	s_cbranch_scc0 .LBB0_675
	s_branch .Lpeel_g3_exit

.Lpeel_g3_exit:
	s_and_b64 vcc, exec, s[20:21]
	s_cbranch_vccz .LBB0_678
	s_barrier

.LBB0_772:
	s_ashr_i32 s25, s24, 31
	s_lshl_b64 s[26:27], s[24:25], 19
	s_add_u32 s26, s42, s26
	s_addc_u32 s27, s43, s27
	s_and_b64 s[28:29], s[8:9], exec
	s_cselect_b32 s25, s27, s31
	s_cselect_b32 s73, s26, s30
	s_ashr_i32 s23, s22, 31
	s_lshl_b64 s[28:29], s[22:23], 19
	s_add_u32 s28, s44, s28
	s_addc_u32 s29, s45, s29
	s_and_b64 s[36:37], s[8:9], exec
	s_cselect_b32 s23, s29, s35
	s_cselect_b32 s74, s28, s34
	s_add_u32 s75, s73, 0x80
	s_addc_u32 s76, s25, 0
	s_add_u32 s78, s34, 0x100
	s_addc_u32 s85, s35, 0
	s_add_u32 s34, s30, 0x40080
	s_addc_u32 s35, s31, 0
	v_lshl_add_u64 v[118:119], s[34:35], 0, v[204:205]
	v_lshl_add_u64 v[120:121], s[34:35], 0, v[206:207]
	s_mov_b32 s86, -2
	s_mov_b64 s[34:35], 0
	s_waitcnt lgkmcnt(0)
	s_add_u32 s4, s30, s34
	s_addc_u32 s5, s31, s35
	s_add_u32 s40, s4, 0x100
	s_addc_u32 s41, s5, 0
	s_add_u32 s38, s78, s34
	s_addc_u32 s39, s85, s35
	s_add_u32 s4, s4, 0x180
	s_addc_u32 s5, s5, 0
	s_add_i32 s65, 0, 0x10000
	s_add_i32 s87, 0, 0x14000
	v_add_u32_e32 v138, s65, v231
	v_add_u32_e32 v162, s87, v231
	ds_read_b128 v[126:129], v138
	ds_read_b128 v[130:133], v138 offset:1024
	ds_read_b128 v[134:137], v138 offset:2048
	ds_read_b128 v[138:141], v138 offset:3072
	ds_read_b128 v[142:145], v162
	ds_read_b128 v[146:149], v162 offset:1024
	ds_read_b128 v[158:161], v162 offset:2048
	ds_read_b128 v[162:165], v162 offset:3072
	s_cmpk_eq_i32 s34, 0x700
	s_cselect_b32 s37, s76, s5
	s_cselect_b32 s36, s75, s4
	s_cselect_b32 s39, s23, s39
	s_cselect_b32 s38, s74, s38
	s_cselect_b32 s41, s25, s41
	s_cselect_b32 s40, s73, s40
	v_lshl_add_u64 v[194:195], v[118:119], 0, s[34:35]
	s_add_i32 m0, s56, 0xc000
	ds_read_b128 v[166:169], v242
	ds_read_b128 v[170:173], v242 offset:1024
	ds_read_b128 v[174:177], v242 offset:2048
	ds_read_b128 v[178:181], v242 offset:3072
	ds_read_b128 v[182:185], v242 offset:4096
	ds_read_b128 v[186:189], v242 offset:5120
	ds_read_b128 v[208:211], v242 offset:6144
	ds_read_b128 v[212:215], v242 offset:7168
	global_load_lds_dwordx4 v[194:195], off
	v_lshl_add_u64 v[194:195], v[120:121], 0, s[34:35]
	s_add_i32 m0, s56, 0xe000
	s_nop 0
	global_load_lds_dwordx4 v[194:195], off
	s_waitcnt vmcnt(8)
	s_waitcnt lgkmcnt(0)
	s_setprio 1
	s_barrier
	v_mfma_f32_16x16x32_bf16 v[154:157], v[126:129], v[166:169], 0
	v_mfma_f32_16x16x32_bf16 v[150:153], v[134:137], v[166:169], 0
	v_mfma_f32_16x16x32_bf16 v[110:113], v[126:129], v[174:177], 0
	v_mfma_f32_16x16x32_bf16 v[106:109], v[134:137], v[174:177], 0
	v_mfma_f32_16x16x32_bf16 v[94:97], v[126:129], v[182:185], 0
	v_mfma_f32_16x16x32_bf16 v[90:93], v[134:137], v[182:185], 0
	v_mfma_f32_16x16x32_bf16 v[78:81], v[126:129], v[208:211], 0
	v_mfma_f32_16x16x32_bf16 v[74:77], v[134:137], v[208:211], 0
	v_mfma_f32_16x16x32_bf16 v[154:157], v[130:133], v[170:173], v[154:157]
	v_mfma_f32_16x16x32_bf16 v[150:153], v[138:141], v[170:173], v[150:153]
	v_mfma_f32_16x16x32_bf16 v[110:113], v[130:133], v[178:181], v[110:113]
	v_mfma_f32_16x16x32_bf16 v[106:109], v[138:141], v[178:181], v[106:109]
	v_mfma_f32_16x16x32_bf16 v[94:97], v[130:133], v[186:189], v[94:97]
	v_mfma_f32_16x16x32_bf16 v[90:93], v[138:141], v[186:189], v[90:93]
	v_mfma_f32_16x16x32_bf16 v[78:81], v[130:133], v[212:215], v[78:81]
	v_mfma_f32_16x16x32_bf16 v[74:77], v[138:141], v[212:215], v[74:77]
	v_mfma_f32_16x16x32_bf16 v[122:125], v[142:145], v[166:169], 0
	v_mfma_f32_16x16x32_bf16 v[114:117], v[158:161], v[166:169], 0
	v_mfma_f32_16x16x32_bf16 v[102:105], v[142:145], v[174:177], 0
	v_mfma_f32_16x16x32_bf16 v[98:101], v[158:161], v[174:177], 0
	v_mfma_f32_16x16x32_bf16 v[86:89], v[142:145], v[182:185], 0
	v_mfma_f32_16x16x32_bf16 v[82:85], v[158:161], v[182:185], 0
	v_mfma_f32_16x16x32_bf16 v[70:73], v[142:145], v[208:211], 0
	v_mfma_f32_16x16x32_bf16 v[66:69], v[158:161], v[208:211], 0
	v_mfma_f32_16x16x32_bf16 v[122:125], v[146:149], v[170:173], v[122:125]
	v_mfma_f32_16x16x32_bf16 v[114:117], v[162:165], v[170:173], v[114:117]
	v_mfma_f32_16x16x32_bf16 v[102:105], v[146:149], v[178:181], v[102:105]
	v_mfma_f32_16x16x32_bf16 v[98:101], v[162:165], v[178:181], v[98:101]
	v_mfma_f32_16x16x32_bf16 v[86:89], v[146:149], v[186:189], v[86:89]
	v_mfma_f32_16x16x32_bf16 v[82:85], v[162:165], v[186:189], v[82:85]
	v_mfma_f32_16x16x32_bf16 v[70:73], v[146:149], v[212:215], v[70:73]
	v_mfma_f32_16x16x32_bf16 v[66:69], v[162:165], v[212:215], v[66:69]
	s_barrier
	s_setprio 0
	s_add_i32 s4, s65, s51
	v_lshl_add_u64 v[194:195], s[38:39], 0, v[0:1]
	s_mov_b32 m0, s4
	ds_read_b128 v[166:169], v242 offset:16384
	ds_read_b128 v[170:173], v242 offset:17408
	ds_read_b128 v[174:177], v242 offset:18432
	ds_read_b128 v[178:181], v242 offset:19456
	ds_read_b128 v[182:185], v242 offset:20480
	ds_read_b128 v[186:189], v242 offset:21504
	ds_read_b128 v[208:211], v242 offset:22528
	ds_read_b128 v[212:215], v242 offset:23552
	global_load_lds_dwordx4 v[194:195], off
	s_add_i32 m0, s4, 0x2000
	s_add_u32 vcc_lo, s38, 0x40000
	v_lshl_add_u64 v[198:199], s[38:39], 0, v[190:191]
	s_addc_u32 vcc_hi, s39, 0
	s_add_i32 s4, s87, s51
	global_load_lds_dwordx4 v[198:199], off
	v_lshl_add_u64 v[216:217], vcc, 0, v[0:1]
	s_mov_b32 m0, s4
	s_nop 0
	global_load_lds_dwordx4 v[216:217], off
	v_lshl_add_u64 v[216:217], vcc, 0, v[190:191]
	s_add_i32 m0, s4, 0x2000
	s_nop 0
	global_load_lds_dwordx4 v[216:217], off
	v_lshl_add_u64 v[216:217], s[40:41], 0, v[202:203]
	s_mov_b32 m0, s56
	s_nop 0
	global_load_lds_dwordx4 v[216:217], off
	v_lshl_add_u64 v[216:217], s[40:41], 0, v[192:193]
	s_mov_b32 m0, s57
	s_nop 0
	global_load_lds_dwordx4 v[216:217], off
	s_waitcnt vmcnt(8)
	s_waitcnt lgkmcnt(0)
	s_setprio 1
	s_barrier
	v_mfma_f32_16x16x32_bf16 v[62:65], v[126:129], v[166:169], 0
	v_mfma_f32_16x16x32_bf16 v[58:61], v[134:137], v[166:169], 0
	v_mfma_f32_16x16x32_bf16 v[46:49], v[126:129], v[174:177], 0
	v_mfma_f32_16x16x32_bf16 v[42:45], v[134:137], v[174:177], 0
	v_mfma_f32_16x16x32_bf16 v[30:33], v[126:129], v[182:185], 0
	v_mfma_f32_16x16x32_bf16 v[26:29], v[134:137], v[182:185], 0
	v_mfma_f32_16x16x32_bf16 v[14:17], v[126:129], v[208:211], 0
	v_mfma_f32_16x16x32_bf16 v[10:13], v[134:137], v[208:211], 0
	v_mfma_f32_16x16x32_bf16 v[62:65], v[130:133], v[170:173], v[62:65]
	v_mfma_f32_16x16x32_bf16 v[58:61], v[138:141], v[170:173], v[58:61]
	v_mfma_f32_16x16x32_bf16 v[46:49], v[130:133], v[178:181], v[46:49]
	v_mfma_f32_16x16x32_bf16 v[42:45], v[138:141], v[178:181], v[42:45]
	v_mfma_f32_16x16x32_bf16 v[30:33], v[130:133], v[186:189], v[30:33]
	v_mfma_f32_16x16x32_bf16 v[26:29], v[138:141], v[186:189], v[26:29]
	v_mfma_f32_16x16x32_bf16 v[14:17], v[130:133], v[212:215], v[14:17]
	v_mfma_f32_16x16x32_bf16 v[10:13], v[138:141], v[212:215], v[10:13]
	v_mfma_f32_16x16x32_bf16 v[54:57], v[142:145], v[166:169], 0
	v_mfma_f32_16x16x32_bf16 v[50:53], v[158:161], v[166:169], 0
	v_mfma_f32_16x16x32_bf16 v[38:41], v[142:145], v[174:177], 0
	v_mfma_f32_16x16x32_bf16 v[34:37], v[158:161], v[174:177], 0
	v_mfma_f32_16x16x32_bf16 v[22:25], v[142:145], v[182:185], 0
	v_mfma_f32_16x16x32_bf16 v[18:21], v[158:161], v[182:185], 0
	v_mfma_f32_16x16x32_bf16 v[6:9], v[142:145], v[208:211], 0
	v_mfma_f32_16x16x32_bf16 v[2:5], v[158:161], v[208:211], 0
	v_mfma_f32_16x16x32_bf16 v[54:57], v[146:149], v[170:173], v[54:57]
	v_mfma_f32_16x16x32_bf16 v[50:53], v[162:165], v[170:173], v[50:53]
	v_mfma_f32_16x16x32_bf16 v[38:41], v[146:149], v[178:181], v[38:41]
	v_mfma_f32_16x16x32_bf16 v[34:37], v[162:165], v[178:181], v[34:37]
	v_mfma_f32_16x16x32_bf16 v[22:25], v[146:149], v[186:189], v[22:25]
	v_mfma_f32_16x16x32_bf16 v[18:21], v[162:165], v[186:189], v[18:21]
	v_mfma_f32_16x16x32_bf16 v[6:9], v[146:149], v[212:215], v[6:9]
	v_mfma_f32_16x16x32_bf16 v[2:5], v[162:165], v[212:215], v[2:5]
	s_barrier
	s_setprio 0
	s_add_i32 s4, 0, 0x18000
	s_add_i32 s5, 0, 0x1c000
	v_add_u32_e32 v138, s4, v231
	v_add_u32_e32 v162, s5, v231
	ds_read_b128 v[126:129], v138
	ds_read_b128 v[130:133], v138 offset:1024
	ds_read_b128 v[134:137], v138 offset:2048
	ds_read_b128 v[138:141], v138 offset:3072
	ds_read_b128 v[142:145], v162
	ds_read_b128 v[146:149], v162 offset:1024
	ds_read_b128 v[158:161], v162 offset:2048
	ds_read_b128 v[162:165], v162 offset:3072
	s_add_u32 s40, s40, 0x40000
	s_addc_u32 s41, s41, 0
	s_mov_b32 m0, s58
	v_lshl_add_u64 v[216:217], s[40:41], 0, v[202:203]
	ds_read_b128 v[166:169], v242 offset:32768
	ds_read_b128 v[170:173], v242 offset:33792
	ds_read_b128 v[174:177], v242 offset:34816
	ds_read_b128 v[178:181], v242 offset:35840
	ds_read_b128 v[182:185], v242 offset:36864
	ds_read_b128 v[186:189], v242 offset:37888
	ds_read_b128 v[208:211], v242 offset:38912
	ds_read_b128 v[212:215], v242 offset:39936
	global_load_lds_dwordx4 v[216:217], off
	v_lshl_add_u64 v[216:217], s[40:41], 0, v[192:193]
	s_mov_b32 m0, s59
	s_nop 0
	global_load_lds_dwordx4 v[216:217], off
	s_waitcnt vmcnt(8)
	s_waitcnt lgkmcnt(0)
	s_setprio 1
	s_barrier
	v_mfma_f32_16x16x32_bf16 v[154:157], v[126:129], v[166:169], v[154:157]
	v_mfma_f32_16x16x32_bf16 v[150:153], v[134:137], v[166:169], v[150:153]
	v_mfma_f32_16x16x32_bf16 v[110:113], v[126:129], v[174:177], v[110:113]
	v_mfma_f32_16x16x32_bf16 v[106:109], v[134:137], v[174:177], v[106:109]
	v_mfma_f32_16x16x32_bf16 v[94:97], v[126:129], v[182:185], v[94:97]
	v_mfma_f32_16x16x32_bf16 v[90:93], v[134:137], v[182:185], v[90:93]
	v_mfma_f32_16x16x32_bf16 v[78:81], v[126:129], v[208:211], v[78:81]
	v_mfma_f32_16x16x32_bf16 v[74:77], v[134:137], v[208:211], v[74:77]
	v_mfma_f32_16x16x32_bf16 v[154:157], v[130:133], v[170:173], v[154:157]
	v_mfma_f32_16x16x32_bf16 v[150:153], v[138:141], v[170:173], v[150:153]
	v_mfma_f32_16x16x32_bf16 v[110:113], v[130:133], v[178:181], v[110:113]
	v_mfma_f32_16x16x32_bf16 v[106:109], v[138:141], v[178:181], v[106:109]
	v_mfma_f32_16x16x32_bf16 v[94:97], v[130:133], v[186:189], v[94:97]
	v_mfma_f32_16x16x32_bf16 v[90:93], v[138:141], v[186:189], v[90:93]
	v_mfma_f32_16x16x32_bf16 v[78:81], v[130:133], v[212:215], v[78:81]
	v_mfma_f32_16x16x32_bf16 v[74:77], v[138:141], v[212:215], v[74:77]
	v_mfma_f32_16x16x32_bf16 v[122:125], v[142:145], v[166:169], v[122:125]
	v_mfma_f32_16x16x32_bf16 v[114:117], v[158:161], v[166:169], v[114:117]
	v_mfma_f32_16x16x32_bf16 v[102:105], v[142:145], v[174:177], v[102:105]
	v_mfma_f32_16x16x32_bf16 v[98:101], v[158:161], v[174:177], v[98:101]
	v_mfma_f32_16x16x32_bf16 v[86:89], v[142:145], v[182:185], v[86:89]
	v_mfma_f32_16x16x32_bf16 v[82:85], v[158:161], v[182:185], v[82:85]
	v_mfma_f32_16x16x32_bf16 v[70:73], v[142:145], v[208:211], v[70:73]
	v_mfma_f32_16x16x32_bf16 v[66:69], v[158:161], v[208:211], v[66:69]
	v_mfma_f32_16x16x32_bf16 v[122:125], v[146:149], v[170:173], v[122:125]
	v_mfma_f32_16x16x32_bf16 v[114:117], v[162:165], v[170:173], v[114:117]
	v_mfma_f32_16x16x32_bf16 v[102:105], v[146:149], v[178:181], v[102:105]
	v_mfma_f32_16x16x32_bf16 v[98:101], v[162:165], v[178:181], v[98:101]
	v_mfma_f32_16x16x32_bf16 v[86:89], v[146:149], v[186:189], v[86:89]
	v_mfma_f32_16x16x32_bf16 v[82:85], v[162:165], v[186:189], v[82:85]
	v_mfma_f32_16x16x32_bf16 v[70:73], v[146:149], v[212:215], v[70:73]
	v_mfma_f32_16x16x32_bf16 v[66:69], v[162:165], v[212:215], v[66:69]
	s_barrier
	s_setprio 0
	s_add_i32 s4, s4, s51
	v_lshl_add_u64 v[194:195], v[194:195], 0, s[90:91]
	s_mov_b32 m0, s4
	ds_read_b128 v[166:169], v242 offset:49152
	ds_read_b128 v[170:173], v242 offset:50176
	ds_read_b128 v[174:177], v242 offset:51200
	ds_read_b128 v[178:181], v242 offset:52224
	ds_read_b128 v[182:185], v242 offset:53248
	ds_read_b128 v[186:189], v242 offset:54272
	ds_read_b128 v[208:211], v242 offset:55296
	ds_read_b128 v[212:215], v242 offset:56320
	global_load_lds_dwordx4 v[194:195], off
	s_add_i32 m0, s4, 0x2000
	s_add_u32 s38, s38, 0x40080
	v_lshl_add_u64 v[194:195], v[198:199], 0, s[90:91]
	s_addc_u32 s39, s39, 0
	s_add_i32 s4, s5, s51
	global_load_lds_dwordx4 v[194:195], off
	v_lshl_add_u64 v[194:195], s[38:39], 0, v[0:1]
	s_mov_b32 m0, s4
	s_nop 0
	global_load_lds_dwordx4 v[194:195], off
	v_lshl_add_u64 v[194:195], s[38:39], 0, v[190:191]
	s_add_i32 m0, s4, 0x2000
	s_nop 0
	global_load_lds_dwordx4 v[194:195], off
	v_lshl_add_u64 v[194:195], s[36:37], 0, v[202:203]
	s_mov_b32 m0, s68
	s_nop 0
	global_load_lds_dwordx4 v[194:195], off
	v_lshl_add_u64 v[194:195], s[36:37], 0, v[192:193]
	s_mov_b32 m0, s69
	s_nop 0
	global_load_lds_dwordx4 v[194:195], off
	s_waitcnt vmcnt(8)
	s_waitcnt lgkmcnt(0)
	s_setprio 1
	s_barrier
	v_mfma_f32_16x16x32_bf16 v[62:65], v[126:129], v[166:169], v[62:65]
	v_mfma_f32_16x16x32_bf16 v[58:61], v[134:137], v[166:169], v[58:61]
	v_mfma_f32_16x16x32_bf16 v[46:49], v[126:129], v[174:177], v[46:49]
	v_mfma_f32_16x16x32_bf16 v[42:45], v[134:137], v[174:177], v[42:45]
	v_mfma_f32_16x16x32_bf16 v[30:33], v[126:129], v[182:185], v[30:33]
	v_mfma_f32_16x16x32_bf16 v[26:29], v[134:137], v[182:185], v[26:29]
	v_mfma_f32_16x16x32_bf16 v[14:17], v[126:129], v[208:211], v[14:17]
	v_mfma_f32_16x16x32_bf16 v[10:13], v[134:137], v[208:211], v[10:13]
	v_mfma_f32_16x16x32_bf16 v[62:65], v[130:133], v[170:173], v[62:65]
	v_mfma_f32_16x16x32_bf16 v[58:61], v[138:141], v[170:173], v[58:61]
	v_mfma_f32_16x16x32_bf16 v[46:49], v[130:133], v[178:181], v[46:49]
	v_mfma_f32_16x16x32_bf16 v[42:45], v[138:141], v[178:181], v[42:45]
	v_mfma_f32_16x16x32_bf16 v[30:33], v[130:133], v[186:189], v[30:33]
	v_mfma_f32_16x16x32_bf16 v[26:29], v[138:141], v[186:189], v[26:29]
	v_mfma_f32_16x16x32_bf16 v[14:17], v[130:133], v[212:215], v[14:17]
	v_mfma_f32_16x16x32_bf16 v[10:13], v[138:141], v[212:215], v[10:13]
	v_mfma_f32_16x16x32_bf16 v[54:57], v[142:145], v[166:169], v[54:57]
	v_mfma_f32_16x16x32_bf16 v[50:53], v[158:161], v[166:169], v[50:53]
	v_mfma_f32_16x16x32_bf16 v[38:41], v[142:145], v[174:177], v[38:41]
	v_mfma_f32_16x16x32_bf16 v[34:37], v[158:161], v[174:177], v[34:37]
	v_mfma_f32_16x16x32_bf16 v[22:25], v[142:145], v[182:185], v[22:25]
	v_mfma_f32_16x16x32_bf16 v[18:21], v[158:161], v[182:185], v[18:21]
	v_mfma_f32_16x16x32_bf16 v[6:9], v[142:145], v[208:211], v[6:9]
	v_mfma_f32_16x16x32_bf16 v[2:5], v[158:161], v[208:211], v[2:5]
	v_mfma_f32_16x16x32_bf16 v[54:57], v[146:149], v[170:173], v[54:57]
	v_mfma_f32_16x16x32_bf16 v[50:53], v[162:165], v[170:173], v[50:53]
	v_mfma_f32_16x16x32_bf16 v[38:41], v[146:149], v[178:181], v[38:41]
	v_mfma_f32_16x16x32_bf16 v[34:37], v[162:165], v[178:181], v[34:37]
	v_mfma_f32_16x16x32_bf16 v[22:25], v[146:149], v[186:189], v[22:25]
	v_mfma_f32_16x16x32_bf16 v[18:21], v[162:165], v[186:189], v[18:21]
	v_mfma_f32_16x16x32_bf16 v[6:9], v[146:149], v[212:215], v[6:9]
	v_mfma_f32_16x16x32_bf16 v[2:5], v[162:165], v[212:215], v[2:5]
	s_barrier
	s_setprio 0
	s_add_i32 s86, s86, 2
	s_add_u32 s34, s34, 0x100
	s_addc_u32 s35, s35, 0
	s_cmp_gt_u32 s86, 13
	s_cbranch_scc0 .LBB0_773
	s_branch .Lpeel_g4_exit

.LBB0_860:
	s_ashr_i32 s25, s24, 31
	s_lshl_b64 s[26:27], s[24:25], 19
	s_add_u32 s26, s42, s26
	s_addc_u32 s27, s43, s27
	s_and_b64 s[28:29], s[8:9], exec
	s_cselect_b32 s25, s27, s31
	s_cselect_b32 s73, s26, s30
	s_ashr_i32 s23, s22, 31
	s_lshl_b64 s[28:29], s[22:23], 19
	s_add_u32 s28, s44, s28
	s_addc_u32 s29, s45, s29
	s_and_b64 s[36:37], s[8:9], exec
	s_cselect_b32 s23, s29, s35
	s_cselect_b32 s74, s28, s34
	s_add_u32 s75, s73, 0x80
	s_addc_u32 s76, s25, 0
	s_add_u32 s36, s30, 0x40080
	s_addc_u32 s37, s31, 0
	s_add_u32 s78, s34, 0x100
	v_lshl_add_u64 v[142:143], s[36:37], 0, v[138:139]
	v_lshl_add_u64 v[144:145], s[36:37], 0, v[140:141]
	s_addc_u32 s85, s35, 0
	s_mov_b32 s86, -2
	s_mov_b64 s[34:35], 0
	s_add_u32 s4, s30, s34
	s_addc_u32 s5, s31, s35
	s_add_u32 s40, s4, 0x100
	s_addc_u32 s41, s5, 0
	s_add_u32 s38, s78, s34
	s_addc_u32 s39, s85, s35
	s_add_u32 s4, s4, 0x180
	s_addc_u32 s5, s5, 0
	s_add_i32 s65, 0, 0x10000
	s_add_i32 s87, 0, 0x14000
	v_add_u32_e32 v162, s65, v152
	v_add_u32_e32 v178, s87, v152
	ds_read_b128 v[146:149], v162
	ds_read_b128 v[154:157], v162 offset:1024
	ds_read_b128 v[158:161], v162 offset:2048
	ds_read_b128 v[162:165], v162 offset:3072
	ds_read_b128 v[166:169], v178
	ds_read_b128 v[170:173], v178 offset:1024
	ds_read_b128 v[174:177], v178 offset:2048
	ds_read_b128 v[178:181], v178 offset:3072
	s_cmpk_eq_i32 s34, 0x700
	s_cselect_b32 s37, s76, s5
	s_cselect_b32 s36, s75, s4
	s_cselect_b32 s39, s23, s39
	s_cselect_b32 s38, s74, s38
	s_cselect_b32 s41, s25, s41
	s_cselect_b32 s40, s73, s40
	v_lshl_add_u64 v[194:195], v[142:143], 0, s[34:35]
	s_add_i32 m0, s56, 0xc000
	ds_read_b128 v[182:185], v153
	ds_read_b128 v[186:189], v153 offset:1024
	ds_read_b128 v[190:193], v153 offset:2048
	ds_read_b128 v[202:205], v153 offset:3072
	ds_read_b128 v[206:209], v153 offset:4096
	ds_read_b128 v[210:213], v153 offset:5120
	ds_read_b128 v[214:217], v153 offset:6144
	ds_read_b128 v[218:221], v153 offset:7168
	global_load_lds_dwordx4 v[194:195], off
	v_lshl_add_u64 v[194:195], v[144:145], 0, s[34:35]
	s_add_i32 m0, s56, 0xe000
	s_nop 0
	global_load_lds_dwordx4 v[194:195], off
	s_waitcnt vmcnt(8)
	s_waitcnt lgkmcnt(0)
	s_setprio 1
	s_barrier
	v_mfma_f32_16x16x32_bf16 v[126:129], v[146:149], v[182:185], 0
	v_mfma_f32_16x16x32_bf16 v[122:125], v[158:161], v[182:185], 0
	v_mfma_f32_16x16x32_bf16 v[110:113], v[146:149], v[190:193], 0
	v_mfma_f32_16x16x32_bf16 v[106:109], v[158:161], v[190:193], 0
	v_mfma_f32_16x16x32_bf16 v[94:97], v[146:149], v[206:209], 0
	v_mfma_f32_16x16x32_bf16 v[90:93], v[158:161], v[206:209], 0
	v_mfma_f32_16x16x32_bf16 v[78:81], v[146:149], v[214:217], 0
	v_mfma_f32_16x16x32_bf16 v[74:77], v[158:161], v[214:217], 0
	v_mfma_f32_16x16x32_bf16 v[126:129], v[154:157], v[186:189], v[126:129]
	v_mfma_f32_16x16x32_bf16 v[122:125], v[162:165], v[186:189], v[122:125]
	v_mfma_f32_16x16x32_bf16 v[110:113], v[154:157], v[202:205], v[110:113]
	v_mfma_f32_16x16x32_bf16 v[106:109], v[162:165], v[202:205], v[106:109]
	v_mfma_f32_16x16x32_bf16 v[94:97], v[154:157], v[210:213], v[94:97]
	v_mfma_f32_16x16x32_bf16 v[90:93], v[162:165], v[210:213], v[90:93]
	v_mfma_f32_16x16x32_bf16 v[78:81], v[154:157], v[218:221], v[78:81]
	v_mfma_f32_16x16x32_bf16 v[74:77], v[162:165], v[218:221], v[74:77]
	v_mfma_f32_16x16x32_bf16 v[118:121], v[166:169], v[182:185], 0
	v_mfma_f32_16x16x32_bf16 v[114:117], v[174:177], v[182:185], 0
	v_mfma_f32_16x16x32_bf16 v[102:105], v[166:169], v[190:193], 0
	v_mfma_f32_16x16x32_bf16 v[98:101], v[174:177], v[190:193], 0
	v_mfma_f32_16x16x32_bf16 v[86:89], v[166:169], v[206:209], 0
	v_mfma_f32_16x16x32_bf16 v[82:85], v[174:177], v[206:209], 0
	v_mfma_f32_16x16x32_bf16 v[70:73], v[166:169], v[214:217], 0
	v_mfma_f32_16x16x32_bf16 v[66:69], v[174:177], v[214:217], 0
	v_mfma_f32_16x16x32_bf16 v[118:121], v[170:173], v[186:189], v[118:121]
	v_mfma_f32_16x16x32_bf16 v[114:117], v[178:181], v[186:189], v[114:117]
	v_mfma_f32_16x16x32_bf16 v[102:105], v[170:173], v[202:205], v[102:105]
	v_mfma_f32_16x16x32_bf16 v[98:101], v[178:181], v[202:205], v[98:101]
	v_mfma_f32_16x16x32_bf16 v[86:89], v[170:173], v[210:213], v[86:89]
	v_mfma_f32_16x16x32_bf16 v[82:85], v[178:181], v[210:213], v[82:85]
	v_mfma_f32_16x16x32_bf16 v[70:73], v[170:173], v[218:221], v[70:73]
	v_mfma_f32_16x16x32_bf16 v[66:69], v[178:181], v[218:221], v[66:69]
	s_barrier
	s_setprio 0
	s_add_i32 s4, s65, s51
	v_lshl_add_u64 v[194:195], s[38:39], 0, v[134:135]
	s_mov_b32 m0, s4
	ds_read_b128 v[182:185], v153 offset:16384
	ds_read_b128 v[186:189], v153 offset:17408
	ds_read_b128 v[190:193], v153 offset:18432
	ds_read_b128 v[202:205], v153 offset:19456
	ds_read_b128 v[206:209], v153 offset:20480
	ds_read_b128 v[210:213], v153 offset:21504
	ds_read_b128 v[214:217], v153 offset:22528
	ds_read_b128 v[218:221], v153 offset:23552
	global_load_lds_dwordx4 v[194:195], off
	s_add_i32 m0, s4, 0x2000
	s_add_u32 vcc_lo, s38, 0x40000
	v_lshl_add_u64 v[198:199], s[38:39], 0, v[130:131]
	s_addc_u32 vcc_hi, s39, 0
	s_add_i32 s4, s87, s51
	global_load_lds_dwordx4 v[198:199], off
	v_lshl_add_u64 v[222:223], vcc, 0, v[134:135]
	s_mov_b32 m0, s4
	s_nop 0
	global_load_lds_dwordx4 v[222:223], off
	v_lshl_add_u64 v[222:223], vcc, 0, v[130:131]
	s_add_i32 m0, s4, 0x2000
	s_nop 0
	global_load_lds_dwordx4 v[222:223], off
	v_lshl_add_u64 v[222:223], s[40:41], 0, v[136:137]
	s_mov_b32 m0, s56
	s_nop 0
	global_load_lds_dwordx4 v[222:223], off
	v_lshl_add_u64 v[222:223], s[40:41], 0, v[132:133]
	s_mov_b32 m0, s57
	s_nop 0
	global_load_lds_dwordx4 v[222:223], off
	s_waitcnt vmcnt(8)
	s_waitcnt lgkmcnt(0)
	s_setprio 1
	s_barrier
	v_mfma_f32_16x16x32_bf16 v[62:65], v[146:149], v[182:185], 0
	v_mfma_f32_16x16x32_bf16 v[58:61], v[158:161], v[182:185], 0
	v_mfma_f32_16x16x32_bf16 v[46:49], v[146:149], v[190:193], 0
	v_mfma_f32_16x16x32_bf16 v[42:45], v[158:161], v[190:193], 0
	v_mfma_f32_16x16x32_bf16 v[30:33], v[146:149], v[206:209], 0
	v_mfma_f32_16x16x32_bf16 v[26:29], v[158:161], v[206:209], 0
	v_mfma_f32_16x16x32_bf16 v[14:17], v[146:149], v[214:217], 0
	v_mfma_f32_16x16x32_bf16 v[10:13], v[158:161], v[214:217], 0
	v_mfma_f32_16x16x32_bf16 v[62:65], v[154:157], v[186:189], v[62:65]
	v_mfma_f32_16x16x32_bf16 v[58:61], v[162:165], v[186:189], v[58:61]
	v_mfma_f32_16x16x32_bf16 v[46:49], v[154:157], v[202:205], v[46:49]
	v_mfma_f32_16x16x32_bf16 v[42:45], v[162:165], v[202:205], v[42:45]
	v_mfma_f32_16x16x32_bf16 v[30:33], v[154:157], v[210:213], v[30:33]
	v_mfma_f32_16x16x32_bf16 v[26:29], v[162:165], v[210:213], v[26:29]
	v_mfma_f32_16x16x32_bf16 v[14:17], v[154:157], v[218:221], v[14:17]
	v_mfma_f32_16x16x32_bf16 v[10:13], v[162:165], v[218:221], v[10:13]
	v_mfma_f32_16x16x32_bf16 v[54:57], v[166:169], v[182:185], 0
	v_mfma_f32_16x16x32_bf16 v[50:53], v[174:177], v[182:185], 0
	v_mfma_f32_16x16x32_bf16 v[38:41], v[166:169], v[190:193], 0
	v_mfma_f32_16x16x32_bf16 v[34:37], v[174:177], v[190:193], 0
	v_mfma_f32_16x16x32_bf16 v[22:25], v[166:169], v[206:209], 0
	v_mfma_f32_16x16x32_bf16 v[18:21], v[174:177], v[206:209], 0
	v_mfma_f32_16x16x32_bf16 v[6:9], v[166:169], v[214:217], 0
	v_mfma_f32_16x16x32_bf16 v[2:5], v[174:177], v[214:217], 0
	v_mfma_f32_16x16x32_bf16 v[54:57], v[170:173], v[186:189], v[54:57]
	v_mfma_f32_16x16x32_bf16 v[50:53], v[178:181], v[186:189], v[50:53]
	v_mfma_f32_16x16x32_bf16 v[38:41], v[170:173], v[202:205], v[38:41]
	v_mfma_f32_16x16x32_bf16 v[34:37], v[178:181], v[202:205], v[34:37]
	v_mfma_f32_16x16x32_bf16 v[22:25], v[170:173], v[210:213], v[22:25]
	v_mfma_f32_16x16x32_bf16 v[18:21], v[178:181], v[210:213], v[18:21]
	v_mfma_f32_16x16x32_bf16 v[6:9], v[170:173], v[218:221], v[6:9]
	v_mfma_f32_16x16x32_bf16 v[2:5], v[178:181], v[218:221], v[2:5]
	s_barrier
	s_setprio 0
	s_add_i32 s4, 0, 0x18000
	s_add_i32 s5, 0, 0x1c000
	v_add_u32_e32 v162, s4, v152
	v_add_u32_e32 v178, s5, v152
	ds_read_b128 v[146:149], v162
	ds_read_b128 v[154:157], v162 offset:1024
	ds_read_b128 v[158:161], v162 offset:2048
	ds_read_b128 v[162:165], v162 offset:3072
	ds_read_b128 v[166:169], v178
	ds_read_b128 v[170:173], v178 offset:1024
	ds_read_b128 v[174:177], v178 offset:2048
	ds_read_b128 v[178:181], v178 offset:3072
	s_add_u32 s40, s40, 0x40000
	s_addc_u32 s41, s41, 0
	s_mov_b32 m0, s58
	v_lshl_add_u64 v[222:223], s[40:41], 0, v[136:137]
	ds_read_b128 v[182:185], v153 offset:32768
	ds_read_b128 v[186:189], v153 offset:33792
	ds_read_b128 v[190:193], v153 offset:34816
	ds_read_b128 v[202:205], v153 offset:35840
	ds_read_b128 v[206:209], v153 offset:36864
	ds_read_b128 v[210:213], v153 offset:37888
	ds_read_b128 v[214:217], v153 offset:38912
	ds_read_b128 v[218:221], v153 offset:39936
	global_load_lds_dwordx4 v[222:223], off
	v_lshl_add_u64 v[222:223], s[40:41], 0, v[132:133]
	s_mov_b32 m0, s59
	s_nop 0
	global_load_lds_dwordx4 v[222:223], off
	s_waitcnt vmcnt(8)
	s_waitcnt lgkmcnt(0)
	s_setprio 1
	s_barrier
	v_mfma_f32_16x16x32_bf16 v[126:129], v[146:149], v[182:185], v[126:129]
	v_mfma_f32_16x16x32_bf16 v[122:125], v[158:161], v[182:185], v[122:125]
	v_mfma_f32_16x16x32_bf16 v[110:113], v[146:149], v[190:193], v[110:113]
	v_mfma_f32_16x16x32_bf16 v[106:109], v[158:161], v[190:193], v[106:109]
	v_mfma_f32_16x16x32_bf16 v[94:97], v[146:149], v[206:209], v[94:97]
	v_mfma_f32_16x16x32_bf16 v[90:93], v[158:161], v[206:209], v[90:93]
	v_mfma_f32_16x16x32_bf16 v[78:81], v[146:149], v[214:217], v[78:81]
	v_mfma_f32_16x16x32_bf16 v[74:77], v[158:161], v[214:217], v[74:77]
	v_mfma_f32_16x16x32_bf16 v[126:129], v[154:157], v[186:189], v[126:129]
	v_mfma_f32_16x16x32_bf16 v[122:125], v[162:165], v[186:189], v[122:125]
	v_mfma_f32_16x16x32_bf16 v[110:113], v[154:157], v[202:205], v[110:113]
	v_mfma_f32_16x16x32_bf16 v[106:109], v[162:165], v[202:205], v[106:109]
	v_mfma_f32_16x16x32_bf16 v[94:97], v[154:157], v[210:213], v[94:97]
	v_mfma_f32_16x16x32_bf16 v[90:93], v[162:165], v[210:213], v[90:93]
	v_mfma_f32_16x16x32_bf16 v[78:81], v[154:157], v[218:221], v[78:81]
	v_mfma_f32_16x16x32_bf16 v[74:77], v[162:165], v[218:221], v[74:77]
	v_mfma_f32_16x16x32_bf16 v[118:121], v[166:169], v[182:185], v[118:121]
	v_mfma_f32_16x16x32_bf16 v[114:117], v[174:177], v[182:185], v[114:117]
	v_mfma_f32_16x16x32_bf16 v[102:105], v[166:169], v[190:193], v[102:105]
	v_mfma_f32_16x16x32_bf16 v[98:101], v[174:177], v[190:193], v[98:101]
	v_mfma_f32_16x16x32_bf16 v[86:89], v[166:169], v[206:209], v[86:89]
	v_mfma_f32_16x16x32_bf16 v[82:85], v[174:177], v[206:209], v[82:85]
	v_mfma_f32_16x16x32_bf16 v[70:73], v[166:169], v[214:217], v[70:73]
	v_mfma_f32_16x16x32_bf16 v[66:69], v[174:177], v[214:217], v[66:69]
	v_mfma_f32_16x16x32_bf16 v[118:121], v[170:173], v[186:189], v[118:121]
	v_mfma_f32_16x16x32_bf16 v[114:117], v[178:181], v[186:189], v[114:117]
	v_mfma_f32_16x16x32_bf16 v[102:105], v[170:173], v[202:205], v[102:105]
	v_mfma_f32_16x16x32_bf16 v[98:101], v[178:181], v[202:205], v[98:101]
	v_mfma_f32_16x16x32_bf16 v[86:89], v[170:173], v[210:213], v[86:89]
	v_mfma_f32_16x16x32_bf16 v[82:85], v[178:181], v[210:213], v[82:85]
	v_mfma_f32_16x16x32_bf16 v[70:73], v[170:173], v[218:221], v[70:73]
	v_mfma_f32_16x16x32_bf16 v[66:69], v[178:181], v[218:221], v[66:69]
	s_barrier
	s_setprio 0
	s_add_i32 s4, s4, s51
	v_lshl_add_u64 v[194:195], v[194:195], 0, s[90:91]
	s_mov_b32 m0, s4
	ds_read_b128 v[182:185], v153 offset:49152
	ds_read_b128 v[186:189], v153 offset:50176
	ds_read_b128 v[190:193], v153 offset:51200
	ds_read_b128 v[202:205], v153 offset:52224
	ds_read_b128 v[206:209], v153 offset:53248
	ds_read_b128 v[210:213], v153 offset:54272
	ds_read_b128 v[214:217], v153 offset:55296
	ds_read_b128 v[218:221], v153 offset:56320
	global_load_lds_dwordx4 v[194:195], off
	s_add_i32 m0, s4, 0x2000
	s_add_u32 s38, s38, 0x40080
	v_lshl_add_u64 v[194:195], v[198:199], 0, s[90:91]
	s_addc_u32 s39, s39, 0
	s_add_i32 s4, s5, s51
	global_load_lds_dwordx4 v[194:195], off
	v_lshl_add_u64 v[194:195], s[38:39], 0, v[134:135]
	s_mov_b32 m0, s4
	s_nop 0
	global_load_lds_dwordx4 v[194:195], off
	v_lshl_add_u64 v[194:195], s[38:39], 0, v[130:131]
	s_add_i32 m0, s4, 0x2000
	s_nop 0
	global_load_lds_dwordx4 v[194:195], off
	v_lshl_add_u64 v[194:195], s[36:37], 0, v[136:137]
	s_mov_b32 m0, s68
	s_nop 0
	global_load_lds_dwordx4 v[194:195], off
	v_lshl_add_u64 v[194:195], s[36:37], 0, v[132:133]
	s_mov_b32 m0, s69
	s_nop 0
	global_load_lds_dwordx4 v[194:195], off
	s_waitcnt vmcnt(8)
	s_waitcnt lgkmcnt(0)
	s_setprio 1
	s_barrier
	v_mfma_f32_16x16x32_bf16 v[62:65], v[146:149], v[182:185], v[62:65]
	v_mfma_f32_16x16x32_bf16 v[58:61], v[158:161], v[182:185], v[58:61]
	v_mfma_f32_16x16x32_bf16 v[46:49], v[146:149], v[190:193], v[46:49]
	v_mfma_f32_16x16x32_bf16 v[42:45], v[158:161], v[190:193], v[42:45]
	v_mfma_f32_16x16x32_bf16 v[30:33], v[146:149], v[206:209], v[30:33]
	v_mfma_f32_16x16x32_bf16 v[26:29], v[158:161], v[206:209], v[26:29]
	v_mfma_f32_16x16x32_bf16 v[14:17], v[146:149], v[214:217], v[14:17]
	v_mfma_f32_16x16x32_bf16 v[10:13], v[158:161], v[214:217], v[10:13]
	v_mfma_f32_16x16x32_bf16 v[62:65], v[154:157], v[186:189], v[62:65]
	v_mfma_f32_16x16x32_bf16 v[58:61], v[162:165], v[186:189], v[58:61]
	v_mfma_f32_16x16x32_bf16 v[46:49], v[154:157], v[202:205], v[46:49]
	v_mfma_f32_16x16x32_bf16 v[42:45], v[162:165], v[202:205], v[42:45]
	v_mfma_f32_16x16x32_bf16 v[30:33], v[154:157], v[210:213], v[30:33]
	v_mfma_f32_16x16x32_bf16 v[26:29], v[162:165], v[210:213], v[26:29]
	v_mfma_f32_16x16x32_bf16 v[14:17], v[154:157], v[218:221], v[14:17]
	v_mfma_f32_16x16x32_bf16 v[10:13], v[162:165], v[218:221], v[10:13]
	v_mfma_f32_16x16x32_bf16 v[54:57], v[166:169], v[182:185], v[54:57]
	v_mfma_f32_16x16x32_bf16 v[50:53], v[174:177], v[182:185], v[50:53]
	v_mfma_f32_16x16x32_bf16 v[38:41], v[166:169], v[190:193], v[38:41]
	v_mfma_f32_16x16x32_bf16 v[34:37], v[174:177], v[190:193], v[34:37]
	v_mfma_f32_16x16x32_bf16 v[22:25], v[166:169], v[206:209], v[22:25]
	v_mfma_f32_16x16x32_bf16 v[18:21], v[174:177], v[206:209], v[18:21]
	v_mfma_f32_16x16x32_bf16 v[6:9], v[166:169], v[214:217], v[6:9]
	v_mfma_f32_16x16x32_bf16 v[2:5], v[174:177], v[214:217], v[2:5]
	v_mfma_f32_16x16x32_bf16 v[54:57], v[170:173], v[186:189], v[54:57]
	v_mfma_f32_16x16x32_bf16 v[50:53], v[178:181], v[186:189], v[50:53]
	v_mfma_f32_16x16x32_bf16 v[38:41], v[170:173], v[202:205], v[38:41]
	v_mfma_f32_16x16x32_bf16 v[34:37], v[178:181], v[202:205], v[34:37]
	v_mfma_f32_16x16x32_bf16 v[22:25], v[170:173], v[210:213], v[22:25]
	v_mfma_f32_16x16x32_bf16 v[18:21], v[178:181], v[210:213], v[18:21]
	v_mfma_f32_16x16x32_bf16 v[6:9], v[170:173], v[218:221], v[6:9]
	v_mfma_f32_16x16x32_bf16 v[2:5], v[178:181], v[218:221], v[2:5]
	s_barrier
	s_setprio 0
	s_add_i32 s86, s86, 2
	s_add_u32 s34, s34, 0x100
	s_addc_u32 s35, s35, 0
	s_cmp_gt_u32 s86, 13
	s_cbranch_scc0 .LBB0_861
	s_branch .Lpeel_g5_exit
.LBB0_861:
	s_add_u32 s4, s30, s34
	s_addc_u32 s5, s31, s35
	s_add_u32 s40, s4, 0x100
	s_addc_u32 s41, s5, 0
	s_add_u32 s38, s78, s34
	s_addc_u32 s39, s85, s35
	s_add_u32 s4, s4, 0x180
	s_addc_u32 s5, s5, 0
	s_add_i32 s65, 0, 0x10000
	s_add_i32 s87, 0, 0x14000
	v_add_u32_e32 v162, s65, v152
	v_add_u32_e32 v178, s87, v152
	ds_read_b128 v[146:149], v162
	ds_read_b128 v[154:157], v162 offset:1024
	ds_read_b128 v[158:161], v162 offset:2048
	ds_read_b128 v[162:165], v162 offset:3072
	ds_read_b128 v[166:169], v178
	ds_read_b128 v[170:173], v178 offset:1024
	ds_read_b128 v[174:177], v178 offset:2048
	ds_read_b128 v[178:181], v178 offset:3072
	s_cmpk_eq_i32 s34, 0x700
	s_cselect_b32 s37, s76, s5
	s_cselect_b32 s36, s75, s4
	s_cselect_b32 s39, s23, s39
	s_cselect_b32 s38, s74, s38
	s_cselect_b32 s41, s25, s41
	s_cselect_b32 s40, s73, s40
	v_lshl_add_u64 v[194:195], v[142:143], 0, s[34:35]
	s_add_i32 m0, s56, 0xc000
	ds_read_b128 v[182:185], v153
	ds_read_b128 v[186:189], v153 offset:1024
	ds_read_b128 v[190:193], v153 offset:2048
	ds_read_b128 v[202:205], v153 offset:3072
	ds_read_b128 v[206:209], v153 offset:4096
	ds_read_b128 v[210:213], v153 offset:5120
	ds_read_b128 v[214:217], v153 offset:6144
	ds_read_b128 v[218:221], v153 offset:7168
	global_load_lds_dwordx4 v[194:195], off
	v_lshl_add_u64 v[194:195], v[144:145], 0, s[34:35]
	s_add_i32 m0, s56, 0xe000
	s_nop 0
	global_load_lds_dwordx4 v[194:195], off
	s_waitcnt vmcnt(8)
	s_waitcnt lgkmcnt(0)
	s_setprio 1
	s_barrier
	v_mfma_f32_16x16x32_bf16 v[126:129], v[146:149], v[182:185], v[126:129]
	v_mfma_f32_16x16x32_bf16 v[122:125], v[158:161], v[182:185], v[122:125]
	v_mfma_f32_16x16x32_bf16 v[110:113], v[146:149], v[190:193], v[110:113]
	v_mfma_f32_16x16x32_bf16 v[106:109], v[158:161], v[190:193], v[106:109]
	v_mfma_f32_16x16x32_bf16 v[94:97], v[146:149], v[206:209], v[94:97]
	v_mfma_f32_16x16x32_bf16 v[90:93], v[158:161], v[206:209], v[90:93]
	v_mfma_f32_16x16x32_bf16 v[78:81], v[146:149], v[214:217], v[78:81]
	v_mfma_f32_16x16x32_bf16 v[74:77], v[158:161], v[214:217], v[74:77]
	v_mfma_f32_16x16x32_bf16 v[126:129], v[154:157], v[186:189], v[126:129]
	v_mfma_f32_16x16x32_bf16 v[122:125], v[162:165], v[186:189], v[122:125]
	v_mfma_f32_16x16x32_bf16 v[110:113], v[154:157], v[202:205], v[110:113]
	v_mfma_f32_16x16x32_bf16 v[106:109], v[162:165], v[202:205], v[106:109]
	v_mfma_f32_16x16x32_bf16 v[94:97], v[154:157], v[210:213], v[94:97]
	v_mfma_f32_16x16x32_bf16 v[90:93], v[162:165], v[210:213], v[90:93]
	v_mfma_f32_16x16x32_bf16 v[78:81], v[154:157], v[218:221], v[78:81]
	v_mfma_f32_16x16x32_bf16 v[74:77], v[162:165], v[218:221], v[74:77]
	v_mfma_f32_16x16x32_bf16 v[118:121], v[166:169], v[182:185], v[118:121]
	v_mfma_f32_16x16x32_bf16 v[114:117], v[174:177], v[182:185], v[114:117]
	v_mfma_f32_16x16x32_bf16 v[102:105], v[166:169], v[190:193], v[102:105]
	v_mfma_f32_16x16x32_bf16 v[98:101], v[174:177], v[190:193], v[98:101]
	v_mfma_f32_16x16x32_bf16 v[86:89], v[166:169], v[206:209], v[86:89]
	v_mfma_f32_16x16x32_bf16 v[82:85], v[174:177], v[206:209], v[82:85]
	v_mfma_f32_16x16x32_bf16 v[70:73], v[166:169], v[214:217], v[70:73]
	v_mfma_f32_16x16x32_bf16 v[66:69], v[174:177], v[214:217], v[66:69]
	v_mfma_f32_16x16x32_bf16 v[118:121], v[170:173], v[186:189], v[118:121]
	v_mfma_f32_16x16x32_bf16 v[114:117], v[178:181], v[186:189], v[114:117]
	v_mfma_f32_16x16x32_bf16 v[102:105], v[170:173], v[202:205], v[102:105]
	v_mfma_f32_16x16x32_bf16 v[98:101], v[178:181], v[202:205], v[98:101]
	v_mfma_f32_16x16x32_bf16 v[86:89], v[170:173], v[210:213], v[86:89]
	v_mfma_f32_16x16x32_bf16 v[82:85], v[178:181], v[210:213], v[82:85]
	v_mfma_f32_16x16x32_bf16 v[70:73], v[170:173], v[218:221], v[70:73]
	v_mfma_f32_16x16x32_bf16 v[66:69], v[178:181], v[218:221], v[66:69]
	s_barrier
	s_setprio 0
	s_add_i32 s4, s65, s51
	v_lshl_add_u64 v[194:195], s[38:39], 0, v[134:135]
	s_mov_b32 m0, s4
	ds_read_b128 v[182:185], v153 offset:16384
	ds_read_b128 v[186:189], v153 offset:17408
	ds_read_b128 v[190:193], v153 offset:18432
	ds_read_b128 v[202:205], v153 offset:19456
	ds_read_b128 v[206:209], v153 offset:20480
	ds_read_b128 v[210:213], v153 offset:21504
	ds_read_b128 v[214:217], v153 offset:22528
	ds_read_b128 v[218:221], v153 offset:23552
	global_load_lds_dwordx4 v[194:195], off
	s_add_i32 m0, s4, 0x2000
	s_add_u32 vcc_lo, s38, 0x40000
	v_lshl_add_u64 v[198:199], s[38:39], 0, v[130:131]
	s_addc_u32 vcc_hi, s39, 0
	s_add_i32 s4, s87, s51
	global_load_lds_dwordx4 v[198:199], off
	v_lshl_add_u64 v[222:223], vcc, 0, v[134:135]
	s_mov_b32 m0, s4
	s_nop 0
	global_load_lds_dwordx4 v[222:223], off
	v_lshl_add_u64 v[222:223], vcc, 0, v[130:131]
	s_add_i32 m0, s4, 0x2000
	s_nop 0
	global_load_lds_dwordx4 v[222:223], off
	v_lshl_add_u64 v[222:223], s[40:41], 0, v[136:137]
	s_mov_b32 m0, s56
	s_nop 0
	global_load_lds_dwordx4 v[222:223], off
	v_lshl_add_u64 v[222:223], s[40:41], 0, v[132:133]
	s_mov_b32 m0, s57
	s_nop 0
	global_load_lds_dwordx4 v[222:223], off
	s_waitcnt vmcnt(8)
	s_waitcnt lgkmcnt(0)
	s_setprio 1
	s_barrier
	v_mfma_f32_16x16x32_bf16 v[62:65], v[146:149], v[182:185], v[62:65]
	v_mfma_f32_16x16x32_bf16 v[58:61], v[158:161], v[182:185], v[58:61]
	v_mfma_f32_16x16x32_bf16 v[46:49], v[146:149], v[190:193], v[46:49]
	v_mfma_f32_16x16x32_bf16 v[42:45], v[158:161], v[190:193], v[42:45]
	v_mfma_f32_16x16x32_bf16 v[30:33], v[146:149], v[206:209], v[30:33]
	v_mfma_f32_16x16x32_bf16 v[26:29], v[158:161], v[206:209], v[26:29]
	v_mfma_f32_16x16x32_bf16 v[14:17], v[146:149], v[214:217], v[14:17]
	v_mfma_f32_16x16x32_bf16 v[10:13], v[158:161], v[214:217], v[10:13]
	v_mfma_f32_16x16x32_bf16 v[62:65], v[154:157], v[186:189], v[62:65]
	v_mfma_f32_16x16x32_bf16 v[58:61], v[162:165], v[186:189], v[58:61]
	v_mfma_f32_16x16x32_bf16 v[46:49], v[154:157], v[202:205], v[46:49]
	v_mfma_f32_16x16x32_bf16 v[42:45], v[162:165], v[202:205], v[42:45]
	v_mfma_f32_16x16x32_bf16 v[30:33], v[154:157], v[210:213], v[30:33]
	v_mfma_f32_16x16x32_bf16 v[26:29], v[162:165], v[210:213], v[26:29]
	v_mfma_f32_16x16x32_bf16 v[14:17], v[154:157], v[218:221], v[14:17]
	v_mfma_f32_16x16x32_bf16 v[10:13], v[162:165], v[218:221], v[10:13]
	v_mfma_f32_16x16x32_bf16 v[54:57], v[166:169], v[182:185], v[54:57]
	v_mfma_f32_16x16x32_bf16 v[50:53], v[174:177], v[182:185], v[50:53]
	v_mfma_f32_16x16x32_bf16 v[38:41], v[166:169], v[190:193], v[38:41]
	v_mfma_f32_16x16x32_bf16 v[34:37], v[174:177], v[190:193], v[34:37]
	v_mfma_f32_16x16x32_bf16 v[22:25], v[166:169], v[206:209], v[22:25]
	v_mfma_f32_16x16x32_bf16 v[18:21], v[174:177], v[206:209], v[18:21]
	v_mfma_f32_16x16x32_bf16 v[6:9], v[166:169], v[214:217], v[6:9]
	v_mfma_f32_16x16x32_bf16 v[2:5], v[174:177], v[214:217], v[2:5]
	v_mfma_f32_16x16x32_bf16 v[54:57], v[170:173], v[186:189], v[54:57]
	v_mfma_f32_16x16x32_bf16 v[50:53], v[178:181], v[186:189], v[50:53]
	v_mfma_f32_16x16x32_bf16 v[38:41], v[170:173], v[202:205], v[38:41]
	v_mfma_f32_16x16x32_bf16 v[34:37], v[178:181], v[202:205], v[34:37]
	v_mfma_f32_16x16x32_bf16 v[22:25], v[170:173], v[210:213], v[22:25]
	v_mfma_f32_16x16x32_bf16 v[18:21], v[178:181], v[210:213], v[18:21]
	v_mfma_f32_16x16x32_bf16 v[6:9], v[170:173], v[218:221], v[6:9]
	v_mfma_f32_16x16x32_bf16 v[2:5], v[178:181], v[218:221], v[2:5]
	s_barrier
	s_setprio 0
	s_add_i32 s4, 0, 0x18000
	s_add_i32 s5, 0, 0x1c000
	v_add_u32_e32 v162, s4, v152
	v_add_u32_e32 v178, s5, v152
	ds_read_b128 v[146:149], v162
	ds_read_b128 v[154:157], v162 offset:1024
	ds_read_b128 v[158:161], v162 offset:2048
	ds_read_b128 v[162:165], v162 offset:3072
	ds_read_b128 v[166:169], v178
	ds_read_b128 v[170:173], v178 offset:1024
	ds_read_b128 v[174:177], v178 offset:2048
	ds_read_b128 v[178:181], v178 offset:3072
	s_add_u32 s40, s40, 0x40000
	s_addc_u32 s41, s41, 0
	s_mov_b32 m0, s58
	v_lshl_add_u64 v[222:223], s[40:41], 0, v[136:137]
	ds_read_b128 v[182:185], v153 offset:32768
	ds_read_b128 v[186:189], v153 offset:33792
	ds_read_b128 v[190:193], v153 offset:34816
	ds_read_b128 v[202:205], v153 offset:35840
	ds_read_b128 v[206:209], v153 offset:36864
	ds_read_b128 v[210:213], v153 offset:37888
	ds_read_b128 v[214:217], v153 offset:38912
	ds_read_b128 v[218:221], v153 offset:39936
	global_load_lds_dwordx4 v[222:223], off
	v_lshl_add_u64 v[222:223], s[40:41], 0, v[132:133]
	s_mov_b32 m0, s59
	s_nop 0
	global_load_lds_dwordx4 v[222:223], off
	s_waitcnt vmcnt(8)
	s_waitcnt lgkmcnt(0)
	s_setprio 1
	s_barrier
	v_mfma_f32_16x16x32_bf16 v[126:129], v[146:149], v[182:185], v[126:129]
	v_mfma_f32_16x16x32_bf16 v[122:125], v[158:161], v[182:185], v[122:125]
	v_mfma_f32_16x16x32_bf16 v[110:113], v[146:149], v[190:193], v[110:113]
	v_mfma_f32_16x16x32_bf16 v[106:109], v[158:161], v[190:193], v[106:109]
	v_mfma_f32_16x16x32_bf16 v[94:97], v[146:149], v[206:209], v[94:97]
	v_mfma_f32_16x16x32_bf16 v[90:93], v[158:161], v[206:209], v[90:93]
	v_mfma_f32_16x16x32_bf16 v[78:81], v[146:149], v[214:217], v[78:81]
	v_mfma_f32_16x16x32_bf16 v[74:77], v[158:161], v[214:217], v[74:77]
	v_mfma_f32_16x16x32_bf16 v[126:129], v[154:157], v[186:189], v[126:129]
	v_mfma_f32_16x16x32_bf16 v[122:125], v[162:165], v[186:189], v[122:125]
	v_mfma_f32_16x16x32_bf16 v[110:113], v[154:157], v[202:205], v[110:113]
	v_mfma_f32_16x16x32_bf16 v[106:109], v[162:165], v[202:205], v[106:109]
	v_mfma_f32_16x16x32_bf16 v[94:97], v[154:157], v[210:213], v[94:97]
	v_mfma_f32_16x16x32_bf16 v[90:93], v[162:165], v[210:213], v[90:93]
	v_mfma_f32_16x16x32_bf16 v[78:81], v[154:157], v[218:221], v[78:81]
	v_mfma_f32_16x16x32_bf16 v[74:77], v[162:165], v[218:221], v[74:77]
	v_mfma_f32_16x16x32_bf16 v[118:121], v[166:169], v[182:185], v[118:121]
	v_mfma_f32_16x16x32_bf16 v[114:117], v[174:177], v[182:185], v[114:117]
	v_mfma_f32_16x16x32_bf16 v[102:105], v[166:169], v[190:193], v[102:105]
	v_mfma_f32_16x16x32_bf16 v[98:101], v[174:177], v[190:193], v[98:101]
	v_mfma_f32_16x16x32_bf16 v[86:89], v[166:169], v[206:209], v[86:89]
	v_mfma_f32_16x16x32_bf16 v[82:85], v[174:177], v[206:209], v[82:85]
	v_mfma_f32_16x16x32_bf16 v[70:73], v[166:169], v[214:217], v[70:73]
	v_mfma_f32_16x16x32_bf16 v[66:69], v[174:177], v[214:217], v[66:69]
	v_mfma_f32_16x16x32_bf16 v[118:121], v[170:173], v[186:189], v[118:121]
	v_mfma_f32_16x16x32_bf16 v[114:117], v[178:181], v[186:189], v[114:117]
	v_mfma_f32_16x16x32_bf16 v[102:105], v[170:173], v[202:205], v[102:105]
	v_mfma_f32_16x16x32_bf16 v[98:101], v[178:181], v[202:205], v[98:101]
	v_mfma_f32_16x16x32_bf16 v[86:89], v[170:173], v[210:213], v[86:89]
	v_mfma_f32_16x16x32_bf16 v[82:85], v[178:181], v[210:213], v[82:85]
	v_mfma_f32_16x16x32_bf16 v[70:73], v[170:173], v[218:221], v[70:73]
	v_mfma_f32_16x16x32_bf16 v[66:69], v[178:181], v[218:221], v[66:69]
	s_barrier
	s_setprio 0
	s_add_i32 s4, s4, s51
	v_lshl_add_u64 v[194:195], v[194:195], 0, s[90:91]
	s_mov_b32 m0, s4
	ds_read_b128 v[182:185], v153 offset:49152
	ds_read_b128 v[186:189], v153 offset:50176
	ds_read_b128 v[190:193], v153 offset:51200
	ds_read_b128 v[202:205], v153 offset:52224
	ds_read_b128 v[206:209], v153 offset:53248
	ds_read_b128 v[210:213], v153 offset:54272
	ds_read_b128 v[214:217], v153 offset:55296
	ds_read_b128 v[218:221], v153 offset:56320
	global_load_lds_dwordx4 v[194:195], off
	s_add_i32 m0, s4, 0x2000
	s_add_u32 s38, s38, 0x40080
	v_lshl_add_u64 v[194:195], v[198:199], 0, s[90:91]
	s_addc_u32 s39, s39, 0
	s_add_i32 s4, s5, s51
	global_load_lds_dwordx4 v[194:195], off
	v_lshl_add_u64 v[194:195], s[38:39], 0, v[134:135]
	s_mov_b32 m0, s4
	s_nop 0
	global_load_lds_dwordx4 v[194:195], off
	v_lshl_add_u64 v[194:195], s[38:39], 0, v[130:131]
	s_add_i32 m0, s4, 0x2000
	s_nop 0
	global_load_lds_dwordx4 v[194:195], off
	v_lshl_add_u64 v[194:195], s[36:37], 0, v[136:137]
	s_mov_b32 m0, s68
	s_nop 0
	global_load_lds_dwordx4 v[194:195], off
	v_lshl_add_u64 v[194:195], s[36:37], 0, v[132:133]
	s_mov_b32 m0, s69
	s_nop 0
	global_load_lds_dwordx4 v[194:195], off
	s_waitcnt vmcnt(8)
	s_waitcnt lgkmcnt(0)
	s_setprio 1
	s_barrier
	v_mfma_f32_16x16x32_bf16 v[62:65], v[146:149], v[182:185], v[62:65]
	v_mfma_f32_16x16x32_bf16 v[58:61], v[158:161], v[182:185], v[58:61]
	v_mfma_f32_16x16x32_bf16 v[46:49], v[146:149], v[190:193], v[46:49]
	v_mfma_f32_16x16x32_bf16 v[42:45], v[158:161], v[190:193], v[42:45]
	v_mfma_f32_16x16x32_bf16 v[30:33], v[146:149], v[206:209], v[30:33]
	v_mfma_f32_16x16x32_bf16 v[26:29], v[158:161], v[206:209], v[26:29]
	v_mfma_f32_16x16x32_bf16 v[14:17], v[146:149], v[214:217], v[14:17]
	v_mfma_f32_16x16x32_bf16 v[10:13], v[158:161], v[214:217], v[10:13]
	v_mfma_f32_16x16x32_bf16 v[62:65], v[154:157], v[186:189], v[62:65]
	v_mfma_f32_16x16x32_bf16 v[58:61], v[162:165], v[186:189], v[58:61]
	v_mfma_f32_16x16x32_bf16 v[46:49], v[154:157], v[202:205], v[46:49]
	v_mfma_f32_16x16x32_bf16 v[42:45], v[162:165], v[202:205], v[42:45]
	v_mfma_f32_16x16x32_bf16 v[30:33], v[154:157], v[210:213], v[30:33]
	v_mfma_f32_16x16x32_bf16 v[26:29], v[162:165], v[210:213], v[26:29]
	v_mfma_f32_16x16x32_bf16 v[14:17], v[154:157], v[218:221], v[14:17]
	v_mfma_f32_16x16x32_bf16 v[10:13], v[162:165], v[218:221], v[10:13]
	v_mfma_f32_16x16x32_bf16 v[54:57], v[166:169], v[182:185], v[54:57]
	v_mfma_f32_16x16x32_bf16 v[50:53], v[174:177], v[182:185], v[50:53]
	v_mfma_f32_16x16x32_bf16 v[38:41], v[166:169], v[190:193], v[38:41]
	v_mfma_f32_16x16x32_bf16 v[34:37], v[174:177], v[190:193], v[34:37]
	v_mfma_f32_16x16x32_bf16 v[22:25], v[166:169], v[206:209], v[22:25]
	v_mfma_f32_16x16x32_bf16 v[18:21], v[174:177], v[206:209], v[18:21]
	v_mfma_f32_16x16x32_bf16 v[6:9], v[166:169], v[214:217], v[6:9]
	v_mfma_f32_16x16x32_bf16 v[2:5], v[174:177], v[214:217], v[2:5]
	v_mfma_f32_16x16x32_bf16 v[54:57], v[170:173], v[186:189], v[54:57]
	v_mfma_f32_16x16x32_bf16 v[50:53], v[178:181], v[186:189], v[50:53]
	v_mfma_f32_16x16x32_bf16 v[38:41], v[170:173], v[202:205], v[38:41]
	v_mfma_f32_16x16x32_bf16 v[34:37], v[178:181], v[202:205], v[34:37]
	v_mfma_f32_16x16x32_bf16 v[22:25], v[170:173], v[210:213], v[22:25]
	v_mfma_f32_16x16x32_bf16 v[18:21], v[178:181], v[210:213], v[18:21]
	v_mfma_f32_16x16x32_bf16 v[6:9], v[170:173], v[218:221], v[6:9]
	v_mfma_f32_16x16x32_bf16 v[2:5], v[178:181], v[218:221], v[2:5]
	s_barrier
	s_setprio 0
	s_add_i32 s86, s86, 2
	s_add_u32 s34, s34, 0x100
	s_addc_u32 s35, s35, 0
	s_cmp_gt_u32 s86, 13
	s_cbranch_scc0 .LBB0_861

.LBB0_914:
	s_ashr_i32 s27, s26, 31
	s_lshl_b64 s[28:29], s[26:27], 21
	s_add_u32 s28, s44, s28
	s_addc_u32 s29, s45, s29
	s_and_b64 s[30:31], s[8:9], exec
	s_cselect_b32 s27, s29, s35
	s_cselect_b32 s72, s28, s34
	s_ashr_i32 s25, s24, 31
	s_lshl_b64 s[30:31], s[24:25], 21
	s_add_u32 s30, s51, s30
	s_addc_u32 s31, s56, s31
	s_and_b64 s[38:39], s[8:9], exec
	s_cselect_b32 s25, s31, s37
	s_cselect_b32 s73, s30, s36
	s_add_u32 s74, s72, 0x80
	s_addc_u32 s75, s27, 0
	s_add_u32 s76, s36, 0x100
	s_addc_u32 s78, s37, 0
	s_add_u32 s36, s34, 0x100080
	s_addc_u32 s37, s35, 0
	v_lshl_add_u64 v[118:119], s[36:37], 0, v[204:205]
	v_lshl_add_u64 v[120:121], s[36:37], 0, v[206:207]
	s_mov_b32 s84, -2
	s_mov_b64 s[36:37], 0
	s_waitcnt lgkmcnt(0)
	s_add_u32 s4, s34, s36
	s_addc_u32 s5, s35, s37
	s_add_u32 s42, s4, 0x100
	s_addc_u32 s43, s5, 0
	s_add_u32 s40, s76, s36
	s_addc_u32 s41, s78, s37
	s_add_u32 s4, s4, 0x180
	s_addc_u32 s5, s5, 0
	s_add_i32 s85, 0, 0x10000
	s_add_i32 vcc_lo, 0, 0x14000
	v_add_u32_e32 v138, s85, v231
	v_add_u32_e32 v162, vcc_lo, v231
	ds_read_b128 v[126:129], v138
	ds_read_b128 v[130:133], v138 offset:1024
	ds_read_b128 v[134:137], v138 offset:2048
	ds_read_b128 v[138:141], v138 offset:3072
	ds_read_b128 v[142:145], v162
	ds_read_b128 v[146:149], v162 offset:1024
	ds_read_b128 v[158:161], v162 offset:2048
	ds_read_b128 v[162:165], v162 offset:3072
	s_cmpk_eq_i32 s36, 0x1f00
	s_cselect_b32 s39, s75, s5
	s_cselect_b32 s38, s74, s4
	s_cselect_b32 s41, s25, s41
	s_cselect_b32 s40, s73, s40
	s_cselect_b32 s43, s27, s43
	s_cselect_b32 s42, s72, s42
	v_lshl_add_u64 v[194:195], v[118:119], 0, s[36:37]
	s_add_i32 m0, s58, 0xc000
	ds_read_b128 v[166:169], v242
	ds_read_b128 v[170:173], v242 offset:1024
	ds_read_b128 v[174:177], v242 offset:2048
	ds_read_b128 v[178:181], v242 offset:3072
	ds_read_b128 v[182:185], v242 offset:4096
	ds_read_b128 v[186:189], v242 offset:5120
	ds_read_b128 v[208:211], v242 offset:6144
	ds_read_b128 v[212:215], v242 offset:7168
	global_load_lds_dwordx4 v[194:195], off
	v_lshl_add_u64 v[194:195], v[120:121], 0, s[36:37]
	s_add_i32 m0, s58, 0xe000
	s_nop 0
	global_load_lds_dwordx4 v[194:195], off
	s_waitcnt vmcnt(8)
	s_waitcnt lgkmcnt(0)
	s_setprio 1
	s_barrier
	v_mfma_f32_16x16x32_bf16 v[154:157], v[126:129], v[166:169], 0
	v_mfma_f32_16x16x32_bf16 v[150:153], v[134:137], v[166:169], 0
	v_mfma_f32_16x16x32_bf16 v[110:113], v[126:129], v[174:177], 0
	v_mfma_f32_16x16x32_bf16 v[106:109], v[134:137], v[174:177], 0
	v_mfma_f32_16x16x32_bf16 v[94:97], v[126:129], v[182:185], 0
	v_mfma_f32_16x16x32_bf16 v[90:93], v[134:137], v[182:185], 0
	v_mfma_f32_16x16x32_bf16 v[78:81], v[126:129], v[208:211], 0
	v_mfma_f32_16x16x32_bf16 v[74:77], v[134:137], v[208:211], 0
	v_mfma_f32_16x16x32_bf16 v[154:157], v[130:133], v[170:173], v[154:157]
	v_mfma_f32_16x16x32_bf16 v[150:153], v[138:141], v[170:173], v[150:153]
	v_mfma_f32_16x16x32_bf16 v[110:113], v[130:133], v[178:181], v[110:113]
	v_mfma_f32_16x16x32_bf16 v[106:109], v[138:141], v[178:181], v[106:109]
	v_mfma_f32_16x16x32_bf16 v[94:97], v[130:133], v[186:189], v[94:97]
	v_mfma_f32_16x16x32_bf16 v[90:93], v[138:141], v[186:189], v[90:93]
	v_mfma_f32_16x16x32_bf16 v[78:81], v[130:133], v[212:215], v[78:81]
	v_mfma_f32_16x16x32_bf16 v[74:77], v[138:141], v[212:215], v[74:77]
	v_mfma_f32_16x16x32_bf16 v[122:125], v[142:145], v[166:169], 0
	v_mfma_f32_16x16x32_bf16 v[114:117], v[158:161], v[166:169], 0
	v_mfma_f32_16x16x32_bf16 v[102:105], v[142:145], v[174:177], 0
	v_mfma_f32_16x16x32_bf16 v[98:101], v[158:161], v[174:177], 0
	v_mfma_f32_16x16x32_bf16 v[86:89], v[142:145], v[182:185], 0
	v_mfma_f32_16x16x32_bf16 v[82:85], v[158:161], v[182:185], 0
	v_mfma_f32_16x16x32_bf16 v[70:73], v[142:145], v[208:211], 0
	v_mfma_f32_16x16x32_bf16 v[66:69], v[158:161], v[208:211], 0
	v_mfma_f32_16x16x32_bf16 v[122:125], v[146:149], v[170:173], v[122:125]
	v_mfma_f32_16x16x32_bf16 v[114:117], v[162:165], v[170:173], v[114:117]
	v_mfma_f32_16x16x32_bf16 v[102:105], v[146:149], v[178:181], v[102:105]
	v_mfma_f32_16x16x32_bf16 v[98:101], v[162:165], v[178:181], v[98:101]
	v_mfma_f32_16x16x32_bf16 v[86:89], v[146:149], v[186:189], v[86:89]
	v_mfma_f32_16x16x32_bf16 v[82:85], v[162:165], v[186:189], v[82:85]
	v_mfma_f32_16x16x32_bf16 v[70:73], v[146:149], v[212:215], v[70:73]
	v_mfma_f32_16x16x32_bf16 v[66:69], v[162:165], v[212:215], v[66:69]
	s_barrier
	s_setprio 0
	s_add_i32 s4, s85, s57
	v_lshl_add_u64 v[194:195], s[40:41], 0, v[0:1]
	s_mov_b32 m0, s4
	ds_read_b128 v[166:169], v242 offset:16384
	ds_read_b128 v[170:173], v242 offset:17408
	ds_read_b128 v[174:177], v242 offset:18432
	ds_read_b128 v[178:181], v242 offset:19456
	ds_read_b128 v[182:185], v242 offset:20480
	ds_read_b128 v[186:189], v242 offset:21504
	ds_read_b128 v[208:211], v242 offset:22528
	ds_read_b128 v[212:215], v242 offset:23552
	global_load_lds_dwordx4 v[194:195], off
	s_add_i32 m0, s4, 0x2000
	s_add_u32 s86, s40, 0x100000
	v_lshl_add_u64 v[198:199], s[40:41], 0, v[190:191]
	s_addc_u32 s87, s41, 0
	s_add_i32 s4, vcc_lo, s57
	global_load_lds_dwordx4 v[198:199], off
	v_lshl_add_u64 v[216:217], s[86:87], 0, v[0:1]
	s_mov_b32 m0, s4
	s_nop 0
	global_load_lds_dwordx4 v[216:217], off
	v_lshl_add_u64 v[216:217], s[86:87], 0, v[190:191]
	s_add_i32 m0, s4, 0x2000
	s_nop 0
	global_load_lds_dwordx4 v[216:217], off
	v_lshl_add_u64 v[216:217], s[42:43], 0, v[202:203]
	s_mov_b32 m0, s58
	s_nop 0
	global_load_lds_dwordx4 v[216:217], off
	v_lshl_add_u64 v[216:217], s[42:43], 0, v[192:193]
	s_mov_b32 m0, s59
	s_nop 0
	global_load_lds_dwordx4 v[216:217], off
	s_waitcnt vmcnt(8)
	s_waitcnt lgkmcnt(0)
	s_setprio 1
	s_barrier
	v_mfma_f32_16x16x32_bf16 v[62:65], v[126:129], v[166:169], 0
	v_mfma_f32_16x16x32_bf16 v[58:61], v[134:137], v[166:169], 0
	v_mfma_f32_16x16x32_bf16 v[46:49], v[126:129], v[174:177], 0
	v_mfma_f32_16x16x32_bf16 v[42:45], v[134:137], v[174:177], 0
	v_mfma_f32_16x16x32_bf16 v[30:33], v[126:129], v[182:185], 0
	v_mfma_f32_16x16x32_bf16 v[26:29], v[134:137], v[182:185], 0
	v_mfma_f32_16x16x32_bf16 v[14:17], v[126:129], v[208:211], 0
	v_mfma_f32_16x16x32_bf16 v[10:13], v[134:137], v[208:211], 0
	v_mfma_f32_16x16x32_bf16 v[62:65], v[130:133], v[170:173], v[62:65]
	v_mfma_f32_16x16x32_bf16 v[58:61], v[138:141], v[170:173], v[58:61]
	v_mfma_f32_16x16x32_bf16 v[46:49], v[130:133], v[178:181], v[46:49]
	v_mfma_f32_16x16x32_bf16 v[42:45], v[138:141], v[178:181], v[42:45]
	v_mfma_f32_16x16x32_bf16 v[30:33], v[130:133], v[186:189], v[30:33]
	v_mfma_f32_16x16x32_bf16 v[26:29], v[138:141], v[186:189], v[26:29]
	v_mfma_f32_16x16x32_bf16 v[14:17], v[130:133], v[212:215], v[14:17]
	v_mfma_f32_16x16x32_bf16 v[10:13], v[138:141], v[212:215], v[10:13]
	v_mfma_f32_16x16x32_bf16 v[54:57], v[142:145], v[166:169], 0
	v_mfma_f32_16x16x32_bf16 v[50:53], v[158:161], v[166:169], 0
	v_mfma_f32_16x16x32_bf16 v[38:41], v[142:145], v[174:177], 0
	v_mfma_f32_16x16x32_bf16 v[34:37], v[158:161], v[174:177], 0
	v_mfma_f32_16x16x32_bf16 v[22:25], v[142:145], v[182:185], 0
	v_mfma_f32_16x16x32_bf16 v[18:21], v[158:161], v[182:185], 0
	v_mfma_f32_16x16x32_bf16 v[6:9], v[142:145], v[208:211], 0
	v_mfma_f32_16x16x32_bf16 v[2:5], v[158:161], v[208:211], 0
	v_mfma_f32_16x16x32_bf16 v[54:57], v[146:149], v[170:173], v[54:57]
	v_mfma_f32_16x16x32_bf16 v[50:53], v[162:165], v[170:173], v[50:53]
	v_mfma_f32_16x16x32_bf16 v[38:41], v[146:149], v[178:181], v[38:41]
	v_mfma_f32_16x16x32_bf16 v[34:37], v[162:165], v[178:181], v[34:37]
	v_mfma_f32_16x16x32_bf16 v[22:25], v[146:149], v[186:189], v[22:25]
	v_mfma_f32_16x16x32_bf16 v[18:21], v[162:165], v[186:189], v[18:21]
	v_mfma_f32_16x16x32_bf16 v[6:9], v[146:149], v[212:215], v[6:9]
	v_mfma_f32_16x16x32_bf16 v[2:5], v[162:165], v[212:215], v[2:5]
	s_barrier
	s_setprio 0
	s_add_i32 s4, 0, 0x18000
	s_add_i32 s5, 0, 0x1c000
	v_add_u32_e32 v138, s4, v231
	v_add_u32_e32 v162, s5, v231
	ds_read_b128 v[126:129], v138
	ds_read_b128 v[130:133], v138 offset:1024
	ds_read_b128 v[134:137], v138 offset:2048
	ds_read_b128 v[138:141], v138 offset:3072
	ds_read_b128 v[142:145], v162
	ds_read_b128 v[146:149], v162 offset:1024
	ds_read_b128 v[158:161], v162 offset:2048
	ds_read_b128 v[162:165], v162 offset:3072
	s_add_u32 s42, s42, 0x100000
	s_addc_u32 s43, s43, 0
	s_mov_b32 m0, s65
	v_lshl_add_u64 v[216:217], s[42:43], 0, v[202:203]
	ds_read_b128 v[166:169], v242 offset:32768
	ds_read_b128 v[170:173], v242 offset:33792
	ds_read_b128 v[174:177], v242 offset:34816
	ds_read_b128 v[178:181], v242 offset:35840
	ds_read_b128 v[182:185], v242 offset:36864
	ds_read_b128 v[186:189], v242 offset:37888
	ds_read_b128 v[208:211], v242 offset:38912
	ds_read_b128 v[212:215], v242 offset:39936
	global_load_lds_dwordx4 v[216:217], off
	v_lshl_add_u64 v[216:217], s[42:43], 0, v[192:193]
	s_mov_b32 m0, s68
	s_nop 0
	global_load_lds_dwordx4 v[216:217], off
	s_waitcnt vmcnt(8)
	s_waitcnt lgkmcnt(0)
	s_setprio 1
	s_barrier
	v_mfma_f32_16x16x32_bf16 v[154:157], v[126:129], v[166:169], v[154:157]
	v_mfma_f32_16x16x32_bf16 v[150:153], v[134:137], v[166:169], v[150:153]
	v_mfma_f32_16x16x32_bf16 v[110:113], v[126:129], v[174:177], v[110:113]
	v_mfma_f32_16x16x32_bf16 v[106:109], v[134:137], v[174:177], v[106:109]
	v_mfma_f32_16x16x32_bf16 v[94:97], v[126:129], v[182:185], v[94:97]
	v_mfma_f32_16x16x32_bf16 v[90:93], v[134:137], v[182:185], v[90:93]
	v_mfma_f32_16x16x32_bf16 v[78:81], v[126:129], v[208:211], v[78:81]
	v_mfma_f32_16x16x32_bf16 v[74:77], v[134:137], v[208:211], v[74:77]
	v_mfma_f32_16x16x32_bf16 v[154:157], v[130:133], v[170:173], v[154:157]
	v_mfma_f32_16x16x32_bf16 v[150:153], v[138:141], v[170:173], v[150:153]
	v_mfma_f32_16x16x32_bf16 v[110:113], v[130:133], v[178:181], v[110:113]
	v_mfma_f32_16x16x32_bf16 v[106:109], v[138:141], v[178:181], v[106:109]
	v_mfma_f32_16x16x32_bf16 v[94:97], v[130:133], v[186:189], v[94:97]
	v_mfma_f32_16x16x32_bf16 v[90:93], v[138:141], v[186:189], v[90:93]
	v_mfma_f32_16x16x32_bf16 v[78:81], v[130:133], v[212:215], v[78:81]
	v_mfma_f32_16x16x32_bf16 v[74:77], v[138:141], v[212:215], v[74:77]
	v_mfma_f32_16x16x32_bf16 v[122:125], v[142:145], v[166:169], v[122:125]
	v_mfma_f32_16x16x32_bf16 v[114:117], v[158:161], v[166:169], v[114:117]
	v_mfma_f32_16x16x32_bf16 v[102:105], v[142:145], v[174:177], v[102:105]
	v_mfma_f32_16x16x32_bf16 v[98:101], v[158:161], v[174:177], v[98:101]
	v_mfma_f32_16x16x32_bf16 v[86:89], v[142:145], v[182:185], v[86:89]
	v_mfma_f32_16x16x32_bf16 v[82:85], v[158:161], v[182:185], v[82:85]
	v_mfma_f32_16x16x32_bf16 v[70:73], v[142:145], v[208:211], v[70:73]
	v_mfma_f32_16x16x32_bf16 v[66:69], v[158:161], v[208:211], v[66:69]
	v_mfma_f32_16x16x32_bf16 v[122:125], v[146:149], v[170:173], v[122:125]
	v_mfma_f32_16x16x32_bf16 v[114:117], v[162:165], v[170:173], v[114:117]
	v_mfma_f32_16x16x32_bf16 v[102:105], v[146:149], v[178:181], v[102:105]
	v_mfma_f32_16x16x32_bf16 v[98:101], v[162:165], v[178:181], v[98:101]
	v_mfma_f32_16x16x32_bf16 v[86:89], v[146:149], v[186:189], v[86:89]
	v_mfma_f32_16x16x32_bf16 v[82:85], v[162:165], v[186:189], v[82:85]
	v_mfma_f32_16x16x32_bf16 v[70:73], v[146:149], v[212:215], v[70:73]
	v_mfma_f32_16x16x32_bf16 v[66:69], v[162:165], v[212:215], v[66:69]
	s_barrier
	s_setprio 0
	s_add_i32 s4, s4, s57
	v_lshl_add_u64 v[194:195], v[194:195], 0, s[90:91]
	s_mov_b32 m0, s4
	ds_read_b128 v[166:169], v242 offset:49152
	ds_read_b128 v[170:173], v242 offset:50176
	ds_read_b128 v[174:177], v242 offset:51200
	ds_read_b128 v[178:181], v242 offset:52224
	ds_read_b128 v[182:185], v242 offset:53248
	ds_read_b128 v[186:189], v242 offset:54272
	ds_read_b128 v[208:211], v242 offset:55296
	ds_read_b128 v[212:215], v242 offset:56320
	global_load_lds_dwordx4 v[194:195], off
	s_add_i32 m0, s4, 0x2000
	s_add_u32 s40, s40, 0x100080
	v_lshl_add_u64 v[194:195], v[198:199], 0, s[90:91]
	s_addc_u32 s41, s41, 0
	s_add_i32 s4, s5, s57
	global_load_lds_dwordx4 v[194:195], off
	v_lshl_add_u64 v[194:195], s[40:41], 0, v[0:1]
	s_mov_b32 m0, s4
	s_nop 0
	global_load_lds_dwordx4 v[194:195], off
	v_lshl_add_u64 v[194:195], s[40:41], 0, v[190:191]
	s_add_i32 m0, s4, 0x2000
	s_nop 0
	global_load_lds_dwordx4 v[194:195], off
	v_lshl_add_u64 v[194:195], s[38:39], 0, v[202:203]
	s_mov_b32 m0, s54
	s_nop 0
	global_load_lds_dwordx4 v[194:195], off
	v_lshl_add_u64 v[194:195], s[38:39], 0, v[192:193]
	s_mov_b32 m0, s55
	s_nop 0
	global_load_lds_dwordx4 v[194:195], off
	s_waitcnt vmcnt(8)
	s_waitcnt lgkmcnt(0)
	s_setprio 1
	s_barrier
	v_mfma_f32_16x16x32_bf16 v[62:65], v[126:129], v[166:169], v[62:65]
	v_mfma_f32_16x16x32_bf16 v[58:61], v[134:137], v[166:169], v[58:61]
	v_mfma_f32_16x16x32_bf16 v[46:49], v[126:129], v[174:177], v[46:49]
	v_mfma_f32_16x16x32_bf16 v[42:45], v[134:137], v[174:177], v[42:45]
	v_mfma_f32_16x16x32_bf16 v[30:33], v[126:129], v[182:185], v[30:33]
	v_mfma_f32_16x16x32_bf16 v[26:29], v[134:137], v[182:185], v[26:29]
	v_mfma_f32_16x16x32_bf16 v[14:17], v[126:129], v[208:211], v[14:17]
	v_mfma_f32_16x16x32_bf16 v[10:13], v[134:137], v[208:211], v[10:13]
	v_mfma_f32_16x16x32_bf16 v[62:65], v[130:133], v[170:173], v[62:65]
	v_mfma_f32_16x16x32_bf16 v[58:61], v[138:141], v[170:173], v[58:61]
	v_mfma_f32_16x16x32_bf16 v[46:49], v[130:133], v[178:181], v[46:49]
	v_mfma_f32_16x16x32_bf16 v[42:45], v[138:141], v[178:181], v[42:45]
	v_mfma_f32_16x16x32_bf16 v[30:33], v[130:133], v[186:189], v[30:33]
	v_mfma_f32_16x16x32_bf16 v[26:29], v[138:141], v[186:189], v[26:29]
	v_mfma_f32_16x16x32_bf16 v[14:17], v[130:133], v[212:215], v[14:17]
	v_mfma_f32_16x16x32_bf16 v[10:13], v[138:141], v[212:215], v[10:13]
	v_mfma_f32_16x16x32_bf16 v[54:57], v[142:145], v[166:169], v[54:57]
	v_mfma_f32_16x16x32_bf16 v[50:53], v[158:161], v[166:169], v[50:53]
	v_mfma_f32_16x16x32_bf16 v[38:41], v[142:145], v[174:177], v[38:41]
	v_mfma_f32_16x16x32_bf16 v[34:37], v[158:161], v[174:177], v[34:37]
	v_mfma_f32_16x16x32_bf16 v[22:25], v[142:145], v[182:185], v[22:25]
	v_mfma_f32_16x16x32_bf16 v[18:21], v[158:161], v[182:185], v[18:21]
	v_mfma_f32_16x16x32_bf16 v[6:9], v[142:145], v[208:211], v[6:9]
	v_mfma_f32_16x16x32_bf16 v[2:5], v[158:161], v[208:211], v[2:5]
	v_mfma_f32_16x16x32_bf16 v[54:57], v[146:149], v[170:173], v[54:57]
	v_mfma_f32_16x16x32_bf16 v[50:53], v[162:165], v[170:173], v[50:53]
	v_mfma_f32_16x16x32_bf16 v[38:41], v[146:149], v[178:181], v[38:41]
	v_mfma_f32_16x16x32_bf16 v[34:37], v[162:165], v[178:181], v[34:37]
	v_mfma_f32_16x16x32_bf16 v[22:25], v[146:149], v[186:189], v[22:25]
	v_mfma_f32_16x16x32_bf16 v[18:21], v[162:165], v[186:189], v[18:21]
	v_mfma_f32_16x16x32_bf16 v[6:9], v[146:149], v[212:215], v[6:9]
	v_mfma_f32_16x16x32_bf16 v[2:5], v[162:165], v[212:215], v[2:5]
	s_barrier
	s_setprio 0
	s_add_i32 s84, s84, 2
	s_add_u32 s36, s36, 0x100
	s_addc_u32 s37, s37, 0
	s_cmp_gt_u32 s84, 61
	s_cbranch_scc0 .LBB0_915
	s_branch .Lpeel_g6a_exit

.LBB0_952:
	s_ashr_i32 s19, s18, 31
	s_lshl_b64 s[20:21], s[18:19], 21
	s_add_u32 s20, s44, s20
	s_addc_u32 s21, s45, s21
	s_and_b64 s[22:23], s[6:7], exec
	s_cselect_b32 s19, s21, s25
	s_cselect_b32 s57, s20, s24
	s_ashr_i32 s17, s16, 31
	s_lshl_b64 s[22:23], s[16:17], 21
	s_add_u32 s22, s51, s22
	s_addc_u32 s23, s56, s23
	s_and_b64 s[28:29], s[6:7], exec
	s_cselect_b32 s17, s23, s27
	s_cselect_b32 s58, s22, s26
	s_add_u32 s59, s57, 0x80
	s_addc_u32 s65, s19, 0
	s_add_u32 s28, s24, 0x100080
	s_addc_u32 s29, s25, 0
	s_add_u32 s68, s26, 0x100
	v_lshl_add_u64 v[122:123], s[28:29], 0, v[208:209]
	v_lshl_add_u64 v[124:125], s[28:29], 0, v[210:211]
	s_addc_u32 s69, s27, 0
	s_mov_b32 s70, -2
	s_mov_b64 s[26:27], 0
	s_add_u32 s4, s24, s26
	s_addc_u32 s5, s25, s27
	s_add_u32 s34, s4, 0x100
	s_addc_u32 s35, s5, 0
	s_add_u32 s30, s68, s26
	s_addc_u32 s31, s69, s27
	s_add_u32 s4, s4, 0x180
	s_addc_u32 s5, s5, 0
	s_add_i32 s71, 0, 0x10000
	s_add_i32 s74, 0, 0x14000
	v_add_u32_e32 v146, s71, v229
	v_add_u32_e32 v162, s74, v229
	ds_read_b128 v[134:137], v146
	ds_read_b128 v[138:141], v146 offset:1024
	ds_read_b128 v[142:145], v146 offset:2048
	ds_read_b128 v[146:149], v146 offset:3072
	ds_read_b128 v[150:153], v162
	ds_read_b128 v[154:157], v162 offset:1024
	ds_read_b128 v[158:161], v162 offset:2048
	ds_read_b128 v[162:165], v162 offset:3072
	s_cmpk_eq_i32 s26, 0x1f00
	s_cselect_b32 s29, s65, s5
	s_cselect_b32 s28, s59, s4
	s_cselect_b32 s31, s17, s31
	s_cselect_b32 s30, s58, s30
	s_cselect_b32 s35, s19, s35
	s_cselect_b32 s34, s57, s34
	v_lshl_add_u64 v[194:195], v[122:123], 0, s[26:27]
	s_add_i32 m0, s37, 0xc000
	ds_read_b128 v[166:169], v231
	ds_read_b128 v[170:173], v231 offset:1024
	ds_read_b128 v[174:177], v231 offset:2048
	ds_read_b128 v[178:181], v231 offset:3072
	ds_read_b128 v[182:185], v231 offset:4096
	ds_read_b128 v[186:189], v231 offset:5120
	ds_read_b128 v[190:193], v231 offset:6144
	ds_read_b128 v[212:215], v231 offset:7168
	global_load_lds_dwordx4 v[194:195], off
	v_lshl_add_u64 v[194:195], v[124:125], 0, s[26:27]
	s_add_i32 m0, s37, 0xe000
	s_nop 0
	global_load_lds_dwordx4 v[194:195], off
	s_waitcnt vmcnt(8)
	s_waitcnt lgkmcnt(0)
	s_setprio 1
	s_barrier
	v_mfma_f32_16x16x32_bf16 v[130:133], v[134:137], v[166:169], 0
	v_mfma_f32_16x16x32_bf16 v[126:129], v[142:145], v[166:169], 0
	v_mfma_f32_16x16x32_bf16 v[110:113], v[134:137], v[174:177], 0
	v_mfma_f32_16x16x32_bf16 v[106:109], v[142:145], v[174:177], 0
	v_mfma_f32_16x16x32_bf16 v[94:97], v[134:137], v[182:185], 0
	v_mfma_f32_16x16x32_bf16 v[90:93], v[142:145], v[182:185], 0
	v_mfma_f32_16x16x32_bf16 v[78:81], v[134:137], v[190:193], 0
	v_mfma_f32_16x16x32_bf16 v[74:77], v[142:145], v[190:193], 0
	v_mfma_f32_16x16x32_bf16 v[130:133], v[138:141], v[170:173], v[130:133]
	v_mfma_f32_16x16x32_bf16 v[126:129], v[146:149], v[170:173], v[126:129]
	v_mfma_f32_16x16x32_bf16 v[110:113], v[138:141], v[178:181], v[110:113]
	v_mfma_f32_16x16x32_bf16 v[106:109], v[146:149], v[178:181], v[106:109]
	v_mfma_f32_16x16x32_bf16 v[94:97], v[138:141], v[186:189], v[94:97]
	v_mfma_f32_16x16x32_bf16 v[90:93], v[146:149], v[186:189], v[90:93]
	v_mfma_f32_16x16x32_bf16 v[78:81], v[138:141], v[212:215], v[78:81]
	v_mfma_f32_16x16x32_bf16 v[74:77], v[146:149], v[212:215], v[74:77]
	v_mfma_f32_16x16x32_bf16 v[118:121], v[150:153], v[166:169], 0
	v_mfma_f32_16x16x32_bf16 v[114:117], v[158:161], v[166:169], 0
	v_mfma_f32_16x16x32_bf16 v[102:105], v[150:153], v[174:177], 0
	v_mfma_f32_16x16x32_bf16 v[98:101], v[158:161], v[174:177], 0
	v_mfma_f32_16x16x32_bf16 v[86:89], v[150:153], v[182:185], 0
	v_mfma_f32_16x16x32_bf16 v[82:85], v[158:161], v[182:185], 0
	v_mfma_f32_16x16x32_bf16 v[70:73], v[150:153], v[190:193], 0
	v_mfma_f32_16x16x32_bf16 v[66:69], v[158:161], v[190:193], 0
	v_mfma_f32_16x16x32_bf16 v[118:121], v[154:157], v[170:173], v[118:121]
	v_mfma_f32_16x16x32_bf16 v[114:117], v[162:165], v[170:173], v[114:117]
	v_mfma_f32_16x16x32_bf16 v[102:105], v[154:157], v[178:181], v[102:105]
	v_mfma_f32_16x16x32_bf16 v[98:101], v[162:165], v[178:181], v[98:101]
	v_mfma_f32_16x16x32_bf16 v[86:89], v[154:157], v[186:189], v[86:89]
	v_mfma_f32_16x16x32_bf16 v[82:85], v[162:165], v[186:189], v[82:85]
	v_mfma_f32_16x16x32_bf16 v[70:73], v[154:157], v[212:215], v[70:73]
	v_mfma_f32_16x16x32_bf16 v[66:69], v[162:165], v[212:215], v[66:69]
	s_barrier
	s_setprio 0
	s_add_i32 s4, s71, s36
	v_lshl_add_u64 v[194:195], s[30:31], 0, v[0:1]
	s_mov_b32 m0, s4
	ds_read_b128 v[166:169], v231 offset:16384
	ds_read_b128 v[170:173], v231 offset:17408
	ds_read_b128 v[174:177], v231 offset:18432
	ds_read_b128 v[178:181], v231 offset:19456
	ds_read_b128 v[182:185], v231 offset:20480
	ds_read_b128 v[186:189], v231 offset:21504
	ds_read_b128 v[190:193], v231 offset:22528
	ds_read_b128 v[212:215], v231 offset:23552
	global_load_lds_dwordx4 v[194:195], off
	s_add_i32 m0, s4, 0x2000
	s_add_u32 s72, s30, 0x100000
	v_lshl_add_u64 v[198:199], s[30:31], 0, v[202:203]
	s_addc_u32 s73, s31, 0
	s_add_i32 s4, s74, s36
	global_load_lds_dwordx4 v[198:199], off
	v_lshl_add_u64 v[216:217], s[72:73], 0, v[0:1]
	s_mov_b32 m0, s4
	s_nop 0
	global_load_lds_dwordx4 v[216:217], off
	v_lshl_add_u64 v[216:217], s[72:73], 0, v[202:203]
	s_add_i32 m0, s4, 0x2000
	s_nop 0
	global_load_lds_dwordx4 v[216:217], off
	v_lshl_add_u64 v[216:217], s[34:35], 0, v[206:207]
	s_mov_b32 m0, s37
	s_nop 0
	global_load_lds_dwordx4 v[216:217], off
	v_lshl_add_u64 v[216:217], s[34:35], 0, v[204:205]
	s_mov_b32 m0, s38
	s_nop 0
	global_load_lds_dwordx4 v[216:217], off
	s_waitcnt vmcnt(8)
	s_waitcnt lgkmcnt(0)
	s_setprio 1
	s_barrier
	v_mfma_f32_16x16x32_bf16 v[62:65], v[134:137], v[166:169], 0
	v_mfma_f32_16x16x32_bf16 v[58:61], v[142:145], v[166:169], 0
	v_mfma_f32_16x16x32_bf16 v[46:49], v[134:137], v[174:177], 0
	v_mfma_f32_16x16x32_bf16 v[42:45], v[142:145], v[174:177], 0
	v_mfma_f32_16x16x32_bf16 v[30:33], v[134:137], v[182:185], 0
	v_mfma_f32_16x16x32_bf16 v[26:29], v[142:145], v[182:185], 0
	v_mfma_f32_16x16x32_bf16 v[14:17], v[134:137], v[190:193], 0
	v_mfma_f32_16x16x32_bf16 v[10:13], v[142:145], v[190:193], 0
	v_mfma_f32_16x16x32_bf16 v[62:65], v[138:141], v[170:173], v[62:65]
	v_mfma_f32_16x16x32_bf16 v[58:61], v[146:149], v[170:173], v[58:61]
	v_mfma_f32_16x16x32_bf16 v[46:49], v[138:141], v[178:181], v[46:49]
	v_mfma_f32_16x16x32_bf16 v[42:45], v[146:149], v[178:181], v[42:45]
	v_mfma_f32_16x16x32_bf16 v[30:33], v[138:141], v[186:189], v[30:33]
	v_mfma_f32_16x16x32_bf16 v[26:29], v[146:149], v[186:189], v[26:29]
	v_mfma_f32_16x16x32_bf16 v[14:17], v[138:141], v[212:215], v[14:17]
	v_mfma_f32_16x16x32_bf16 v[10:13], v[146:149], v[212:215], v[10:13]
	v_mfma_f32_16x16x32_bf16 v[54:57], v[150:153], v[166:169], 0
	v_mfma_f32_16x16x32_bf16 v[50:53], v[158:161], v[166:169], 0
	v_mfma_f32_16x16x32_bf16 v[38:41], v[150:153], v[174:177], 0
	v_mfma_f32_16x16x32_bf16 v[34:37], v[158:161], v[174:177], 0
	v_mfma_f32_16x16x32_bf16 v[22:25], v[150:153], v[182:185], 0
	v_mfma_f32_16x16x32_bf16 v[18:21], v[158:161], v[182:185], 0
	v_mfma_f32_16x16x32_bf16 v[6:9], v[150:153], v[190:193], 0
	v_mfma_f32_16x16x32_bf16 v[2:5], v[158:161], v[190:193], 0
	v_mfma_f32_16x16x32_bf16 v[54:57], v[154:157], v[170:173], v[54:57]
	v_mfma_f32_16x16x32_bf16 v[50:53], v[162:165], v[170:173], v[50:53]
	v_mfma_f32_16x16x32_bf16 v[38:41], v[154:157], v[178:181], v[38:41]
	v_mfma_f32_16x16x32_bf16 v[34:37], v[162:165], v[178:181], v[34:37]
	v_mfma_f32_16x16x32_bf16 v[22:25], v[154:157], v[186:189], v[22:25]
	v_mfma_f32_16x16x32_bf16 v[18:21], v[162:165], v[186:189], v[18:21]
	v_mfma_f32_16x16x32_bf16 v[6:9], v[154:157], v[212:215], v[6:9]
	v_mfma_f32_16x16x32_bf16 v[2:5], v[162:165], v[212:215], v[2:5]
	s_barrier
	s_setprio 0
	s_add_i32 s4, 0, 0x18000
	s_add_i32 s5, 0, 0x1c000
	v_add_u32_e32 v146, s4, v229
	v_add_u32_e32 v162, s5, v229
	ds_read_b128 v[134:137], v146
	ds_read_b128 v[138:141], v146 offset:1024
	ds_read_b128 v[142:145], v146 offset:2048
	ds_read_b128 v[146:149], v146 offset:3072
	ds_read_b128 v[150:153], v162
	ds_read_b128 v[154:157], v162 offset:1024
	ds_read_b128 v[158:161], v162 offset:2048
	ds_read_b128 v[162:165], v162 offset:3072
	s_add_u32 s34, s34, 0x100000
	s_addc_u32 s35, s35, 0
	s_mov_b32 m0, s39
	v_lshl_add_u64 v[216:217], s[34:35], 0, v[206:207]
	ds_read_b128 v[166:169], v231 offset:32768
	ds_read_b128 v[170:173], v231 offset:33792
	ds_read_b128 v[174:177], v231 offset:34816
	ds_read_b128 v[178:181], v231 offset:35840
	ds_read_b128 v[182:185], v231 offset:36864
	ds_read_b128 v[186:189], v231 offset:37888
	ds_read_b128 v[190:193], v231 offset:38912
	ds_read_b128 v[212:215], v231 offset:39936
	global_load_lds_dwordx4 v[216:217], off
	v_lshl_add_u64 v[216:217], s[34:35], 0, v[204:205]
	s_mov_b32 m0, s40
	s_nop 0
	global_load_lds_dwordx4 v[216:217], off
	s_waitcnt vmcnt(8)
	s_waitcnt lgkmcnt(0)
	s_setprio 1
	s_barrier
	v_mfma_f32_16x16x32_bf16 v[130:133], v[134:137], v[166:169], v[130:133]
	v_mfma_f32_16x16x32_bf16 v[126:129], v[142:145], v[166:169], v[126:129]
	v_mfma_f32_16x16x32_bf16 v[110:113], v[134:137], v[174:177], v[110:113]
	v_mfma_f32_16x16x32_bf16 v[106:109], v[142:145], v[174:177], v[106:109]
	v_mfma_f32_16x16x32_bf16 v[94:97], v[134:137], v[182:185], v[94:97]
	v_mfma_f32_16x16x32_bf16 v[90:93], v[142:145], v[182:185], v[90:93]
	v_mfma_f32_16x16x32_bf16 v[78:81], v[134:137], v[190:193], v[78:81]
	v_mfma_f32_16x16x32_bf16 v[74:77], v[142:145], v[190:193], v[74:77]
	v_mfma_f32_16x16x32_bf16 v[130:133], v[138:141], v[170:173], v[130:133]
	v_mfma_f32_16x16x32_bf16 v[126:129], v[146:149], v[170:173], v[126:129]
	v_mfma_f32_16x16x32_bf16 v[110:113], v[138:141], v[178:181], v[110:113]
	v_mfma_f32_16x16x32_bf16 v[106:109], v[146:149], v[178:181], v[106:109]
	v_mfma_f32_16x16x32_bf16 v[94:97], v[138:141], v[186:189], v[94:97]
	v_mfma_f32_16x16x32_bf16 v[90:93], v[146:149], v[186:189], v[90:93]
	v_mfma_f32_16x16x32_bf16 v[78:81], v[138:141], v[212:215], v[78:81]
	v_mfma_f32_16x16x32_bf16 v[74:77], v[146:149], v[212:215], v[74:77]
	v_mfma_f32_16x16x32_bf16 v[118:121], v[150:153], v[166:169], v[118:121]
	v_mfma_f32_16x16x32_bf16 v[114:117], v[158:161], v[166:169], v[114:117]
	v_mfma_f32_16x16x32_bf16 v[102:105], v[150:153], v[174:177], v[102:105]
	v_mfma_f32_16x16x32_bf16 v[98:101], v[158:161], v[174:177], v[98:101]
	v_mfma_f32_16x16x32_bf16 v[86:89], v[150:153], v[182:185], v[86:89]
	v_mfma_f32_16x16x32_bf16 v[82:85], v[158:161], v[182:185], v[82:85]
	v_mfma_f32_16x16x32_bf16 v[70:73], v[150:153], v[190:193], v[70:73]
	v_mfma_f32_16x16x32_bf16 v[66:69], v[158:161], v[190:193], v[66:69]
	v_mfma_f32_16x16x32_bf16 v[118:121], v[154:157], v[170:173], v[118:121]
	v_mfma_f32_16x16x32_bf16 v[114:117], v[162:165], v[170:173], v[114:117]
	v_mfma_f32_16x16x32_bf16 v[102:105], v[154:157], v[178:181], v[102:105]
	v_mfma_f32_16x16x32_bf16 v[98:101], v[162:165], v[178:181], v[98:101]
	v_mfma_f32_16x16x32_bf16 v[86:89], v[154:157], v[186:189], v[86:89]
	v_mfma_f32_16x16x32_bf16 v[82:85], v[162:165], v[186:189], v[82:85]
	v_mfma_f32_16x16x32_bf16 v[70:73], v[154:157], v[212:215], v[70:73]
	v_mfma_f32_16x16x32_bf16 v[66:69], v[162:165], v[212:215], v[66:69]
	s_barrier
	s_setprio 0
	s_add_i32 s4, s4, s36
	v_lshl_add_u64 v[194:195], v[194:195], 0, s[90:91]
	s_mov_b32 m0, s4
	ds_read_b128 v[166:169], v231 offset:49152
	ds_read_b128 v[170:173], v231 offset:50176
	ds_read_b128 v[174:177], v231 offset:51200
	ds_read_b128 v[178:181], v231 offset:52224
	ds_read_b128 v[182:185], v231 offset:53248
	ds_read_b128 v[186:189], v231 offset:54272
	ds_read_b128 v[190:193], v231 offset:55296
	ds_read_b128 v[212:215], v231 offset:56320
	global_load_lds_dwordx4 v[194:195], off
	s_add_i32 m0, s4, 0x2000
	s_add_u32 s30, s30, 0x100080
	v_lshl_add_u64 v[194:195], v[198:199], 0, s[90:91]
	s_addc_u32 s31, s31, 0
	s_add_i32 s4, s5, s36
	global_load_lds_dwordx4 v[194:195], off
	v_lshl_add_u64 v[194:195], s[30:31], 0, v[0:1]
	s_mov_b32 m0, s4
	s_nop 0
	global_load_lds_dwordx4 v[194:195], off
	v_lshl_add_u64 v[194:195], s[30:31], 0, v[202:203]
	s_add_i32 m0, s4, 0x2000
	s_nop 0
	global_load_lds_dwordx4 v[194:195], off
	v_lshl_add_u64 v[194:195], s[28:29], 0, v[206:207]
	s_mov_b32 m0, s41
	s_nop 0
	global_load_lds_dwordx4 v[194:195], off
	v_lshl_add_u64 v[194:195], s[28:29], 0, v[204:205]
	s_mov_b32 m0, s42
	s_nop 0
	global_load_lds_dwordx4 v[194:195], off
	s_waitcnt vmcnt(8)
	s_waitcnt lgkmcnt(0)
	s_setprio 1
	s_barrier
	v_mfma_f32_16x16x32_bf16 v[62:65], v[134:137], v[166:169], v[62:65]
	v_mfma_f32_16x16x32_bf16 v[58:61], v[142:145], v[166:169], v[58:61]
	v_mfma_f32_16x16x32_bf16 v[46:49], v[134:137], v[174:177], v[46:49]
	v_mfma_f32_16x16x32_bf16 v[42:45], v[142:145], v[174:177], v[42:45]
	v_mfma_f32_16x16x32_bf16 v[30:33], v[134:137], v[182:185], v[30:33]
	v_mfma_f32_16x16x32_bf16 v[26:29], v[142:145], v[182:185], v[26:29]
	v_mfma_f32_16x16x32_bf16 v[14:17], v[134:137], v[190:193], v[14:17]
	v_mfma_f32_16x16x32_bf16 v[10:13], v[142:145], v[190:193], v[10:13]
	v_mfma_f32_16x16x32_bf16 v[62:65], v[138:141], v[170:173], v[62:65]
	v_mfma_f32_16x16x32_bf16 v[58:61], v[146:149], v[170:173], v[58:61]
	v_mfma_f32_16x16x32_bf16 v[46:49], v[138:141], v[178:181], v[46:49]
	v_mfma_f32_16x16x32_bf16 v[42:45], v[146:149], v[178:181], v[42:45]
	v_mfma_f32_16x16x32_bf16 v[30:33], v[138:141], v[186:189], v[30:33]
	v_mfma_f32_16x16x32_bf16 v[26:29], v[146:149], v[186:189], v[26:29]
	v_mfma_f32_16x16x32_bf16 v[14:17], v[138:141], v[212:215], v[14:17]
	v_mfma_f32_16x16x32_bf16 v[10:13], v[146:149], v[212:215], v[10:13]
	v_mfma_f32_16x16x32_bf16 v[54:57], v[150:153], v[166:169], v[54:57]
	v_mfma_f32_16x16x32_bf16 v[50:53], v[158:161], v[166:169], v[50:53]
	v_mfma_f32_16x16x32_bf16 v[38:41], v[150:153], v[174:177], v[38:41]
	v_mfma_f32_16x16x32_bf16 v[34:37], v[158:161], v[174:177], v[34:37]
	v_mfma_f32_16x16x32_bf16 v[22:25], v[150:153], v[182:185], v[22:25]
	v_mfma_f32_16x16x32_bf16 v[18:21], v[158:161], v[182:185], v[18:21]
	v_mfma_f32_16x16x32_bf16 v[6:9], v[150:153], v[190:193], v[6:9]
	v_mfma_f32_16x16x32_bf16 v[2:5], v[158:161], v[190:193], v[2:5]
	v_mfma_f32_16x16x32_bf16 v[54:57], v[154:157], v[170:173], v[54:57]
	v_mfma_f32_16x16x32_bf16 v[50:53], v[162:165], v[170:173], v[50:53]
	v_mfma_f32_16x16x32_bf16 v[38:41], v[154:157], v[178:181], v[38:41]
	v_mfma_f32_16x16x32_bf16 v[34:37], v[162:165], v[178:181], v[34:37]
	v_mfma_f32_16x16x32_bf16 v[22:25], v[154:157], v[186:189], v[22:25]
	v_mfma_f32_16x16x32_bf16 v[18:21], v[162:165], v[186:189], v[18:21]
	v_mfma_f32_16x16x32_bf16 v[6:9], v[154:157], v[212:215], v[6:9]
	v_mfma_f32_16x16x32_bf16 v[2:5], v[162:165], v[212:215], v[2:5]
	s_barrier
	s_setprio 0
	s_add_i32 s70, s70, 2
	s_add_u32 s26, s26, 0x100
	s_addc_u32 s27, s27, 0
	s_cmp_gt_u32 s70, 61
	s_cbranch_scc0 .LBB0_953
	s_branch .Lpeel_g6b_exit

.Lpeel_g6b_exit:
	s_and_b64 vcc, exec, s[14:15]
	s_cbranch_vccz .LBB0_956
	s_barrier
